# mode-0 (up/SwiGLU) GEMM: LDS tile image re-laid as full 128-B rows (8-row x 128-B LDS-DMA pieces, XOR-swizzled chunks) instead of 16-row x 64-B sub-tiles; plus K-loop trims
# speedup vs baseline: 1.0047x; 1.0047x over previous
; __device__ __forceinline__ int otid() { int t = threadIdx.x; asm volatile("" : "+v"(t)); return t; }
; #define PG8_STAGE(bufoff, gbase, voff) do { _Pragma("unroll") for (int _i = 0; _i < 2; ++_i) \
;         __builtin_amdgcn_global_load_lds((const unsigned*)((const char*)(gbase) + (voff)[_i]), (LAS unsigned*)(lds + (bufoff) + ldsw + _i * 8192), 16, 0, 0); } while (0)
; #define PG8_WAIT_V(n) asm volatile("s_waitcnt vmcnt(" #n ")" ::: "memory")
; #define PG8_BAR __builtin_amdgcn_s_barrier()
; template <int MODE, class EpiT, class Sched>
; __device__ __forceinline__ void gemm_phase(LAS unsigned char* lds, const Gemm g, const Sched& S, const EpiT& E) {
;     const int tid = otid(), wid = __builtin_amdgcn_readfirstlane(tid >> 6), lane = tid & 63, wr = wid >> 2, wc = wid & 3, fr = lane & 15, fq = lane >> 4;
;     const int K = g.K, nt = K / BK;
;     unsigned voffA[2], voffB[2];
; #pragma unroll
;     for (int i = 0; i < 2; ++i) { int R, C; stage_rc(tid * 16 + i * 8192, R, C); voffA[i] = (unsigned)(R * K + C) * 2u; voffB[i] = (unsigned)(R * K + C) * 2u; }
;     const size_t kstep = (size_t)(BK * 2);
;     const size_t hstep = (size_t)HALF * K * 2;
;     const size_t tstep = 2 * hstep;
;     const unsigned ldsw = (unsigned)wid * 1024u;
;     const int aoff = lds_byte(wr * 64 + fr, fq * 8), boff = lds_byte(wc * 32 + fr, fq * 8);
;     ...
;     const char* cA = (const char*)g.A + (size_t)cur.pm * tstep; const char* cB = (const char*)g.Bt + (size_t)cur.pn * tstep;
;     PG8_STAGE(PG8_SB(0, 0), cB, voffB); PG8_STAGE(PG8_SA(0, 0), cA, voffA); PG8_STAGE(PG8_SB(0, 1), cB + hstep, voffB); PG8_STAGE(PG8_SA(0, 1), cA + hstep, voffA);
;     if (wr == 1) PG8_BAR;
;     PG8_WAIT_V(4); PG8_BAR;
;     PG8_STAGE(PG8_SB(1, 0), cB + kstep, voffB); PG8_STAGE(PG8_SA(1, 0), cA + kstep, voffA); PG8_STAGE(PG8_SB(1, 1), cB + hstep + kstep, voffB);
.LBB0_321:
	s_or_b64 exec, exec, s[4:5]
	v_bfe_i32 v2, v50, 27, 1
	v_lshlrev_b32_e32 v5, 4, v50
	v_lshrrev_b32_e32 v2, 22, v2
	v_add_u32_e32 v2, v5, v2
	v_and_b32_e32 v2, 0xfffffc00, v2
	s_waitcnt lgkmcnt(0)
	v_ashrrev_i32_e32 v0, 31, v50
	v_sub_u32_e32 v2, v5, v2
	v_lshrrev_b32_e32 v0, 26, v0
	v_lshrrev_b32_e32 v3, 4, v2
	v_add_u32_e32 v0, v50, v0
	v_bitop3_b32 v3, v3, v2, 32 bitop3:0x6c
	v_ashrrev_i32_e32 v2, 31, v2
	v_ashrrev_i32_e32 v0, 6, v0
	v_lshrrev_b32_e32 v2, 26, v2
	v_lshlrev_b32_e32 v4, 3, v0
	v_add_u32_e32 v2, v3, v2
	v_and_b32_e32 v4, 0x7ffffff0, v4
	v_ashrrev_i32_e32 v6, 6, v2
	v_lshlrev_b32_e32 v0, 5, v0
	v_add_u32_e32 v5, 0x2000, v5
	v_add_u32_e32 v4, v6, v4
	v_and_b32_e32 v2, 32, v0
	v_mul_i32_i24_e32 v0, 64, v6
	v_ashrrev_i32_e32 v6, 31, v5
	v_lshrrev_b32_e32 v6, 22, v6
	v_add_u32_e32 v6, v5, v6
	v_ashrrev_i32_e32 v6, 10, v6
	v_mul_i32_i24_e32 v7, 0x400, v6
	v_sub_u32_e32 v5, v5, v7
	v_lshrrev_b32_e32 v7, 4, v5
	v_bitop3_b32 v7, v7, v5, 32 bitop3:0x6c
	v_ashrrev_i32_e32 v8, 31, v7
	v_lshrrev_b32_e32 v8, 26, v8
	s_ashr_i32 s2, s3, 6
	v_lshlrev_b32_e32 v5, 3, v6
	v_add_u32_e32 v8, v7, v8
	s_lshl_b32 s24, s16, 9
	v_sub_u32_e32 v0, v3, v0
	v_and_b32_e32 v5, 0x7ffffff0, v5
	v_ashrrev_i32_e32 v9, 6, v8
	s_ashr_i32 s22, s3, 8
	s_lshl_b32 s21, s16, 8
	s_lshl_b32 s46, s2, 10
	s_mul_i32 s10, s24, s8
	v_ashrrev_i16_sdwa v0, v202, sext(v0) dst_sel:DWORD dst_unused:UNUSED_PAD src0_sel:DWORD src1_sel:BYTE_0
	v_mul_lo_u32 v4, v4, s16
	v_add_u32_e32 v9, v9, v5
	v_lshlrev_b32_e32 v5, 5, v6
	v_and_b32_e32 v6, 0xc0, v8
	s_mul_hi_i32 s11, s24, s8
	s_add_u32 s10, s18, s10
	v_bfe_i32 v3, v0, 0, 16
	v_or_b32_e32 v0, v4, v2
	v_sub_u32_e32 v6, v7, v6
	s_addc_u32 s11, s19, s11
	s_add_i32 s47, s46, 0
	v_add_lshl_u32 v0, v0, v3, 1
	v_and_b32_e32 v5, 32, v5
	v_ashrrev_i16_sdwa v6, v202, sext(v6) dst_sel:DWORD dst_unused:UNUSED_PAD src0_sel:DWORD src1_sel:BYTE_0
	v_mul_lo_u32 v7, v9, s16
	s_add_i32 m0, s47, 0x10000
	v_bfe_i32 v6, v6, 0, 16
	v_or_b32_e32 v8, v7, v5
	v_lshrrev_b32_e32 v249, 3, v50
	v_mul_lo_u32 v249, v249, s16
	v_and_b32_e32 v250, 7, v50
	v_bfe_u32 v251, v50, 4, 3
	v_xor_b32_e32 v250, v250, v251
	v_lshlrev_b32_e32 v250, 4, v250
	v_lshl_add_u32 v0, v249, 1, v250
	s_lshl_b32 s100, s16, 7
	s_barrier
	s_mul_i32 s5, s24, s9
	global_load_lds_dwordx4 v0, s[10:11]
	s_add_i32 m0, s47, 0x12000
	v_add_u32_e32 v130, s100, v0
	s_mul_hi_i32 s4, s24, s9
	s_add_u32 s12, s48, s5
	global_load_lds_dwordx4 v130, s[10:11]
	s_addc_u32 s13, s49, s4
	s_mov_b32 m0, s47
	s_add_i32 s50, s47, 0x2000
	global_load_lds_dwordx4 v0, s[12:13]
	s_mov_b32 m0, s50
	s_add_u32 s4, s10, s21
	global_load_lds_dwordx4 v130, s[12:13]
	s_addc_u32 s5, s11, 0
	s_add_i32 m0, s47, 0x14000
	s_nop 0
	global_load_lds_dwordx4 v0, s[4:5]
	s_add_i32 m0, s47, 0x16000
	s_add_u32 s28, s12, s21
	s_addc_u32 s29, s13, 0
	s_add_i32 s51, s47, 0x4000
	global_load_lds_dwordx4 v130, s[4:5]
	s_mov_b32 m0, s51
	s_add_i32 s52, s47, 0x6000
	global_load_lds_dwordx4 v0, s[28:29]
	s_mov_b32 m0, s52
	s_cmp_lg_u32 s22, 1
	global_load_lds_dwordx4 v130, s[28:29]
	s_cbranch_scc1 .LBB0_323
	s_barrier
; #define PG8_STAGE(bufoff, gbase, voff) do { _Pragma("unroll") for (int _i = 0; _i < 2; ++_i) \
;         __builtin_amdgcn_global_load_lds((const unsigned*)((const char*)(gbase) + (voff)[_i]), (LAS unsigned*)(lds + (bufoff) + ldsw + _i * 8192), 16, 0, 0); } while (0)
; #define PG8_WAIT_V(n) asm volatile("s_waitcnt vmcnt(" #n ")" ::: "memory")
; #define PG8_BAR __builtin_amdgcn_s_barrier()
; template <int MODE, class EpiT, class Sched>
; __device__ __forceinline__ void gemm_phase(LAS unsigned char* lds, const Gemm g, const Sched& S, const EpiT& E) {
;     ...
;     for (int i = 0; i < 2; ++i) { int R, C; stage_rc(tid * 16 + i * 8192, R, C); voffA[i] = (unsigned)(R * K + C) * 2u; voffB[i] = (unsigned)(R * K + C) * 2u; }
;     const size_t kstep = (size_t)(BK * 2);
;     const size_t hstep = (size_t)HALF * K * 2;
;     const size_t tstep = 2 * hstep;
;     const unsigned ldsw = (unsigned)wid * 1024u;
;     const int aoff = lds_byte(wr * 64 + fr, fq * 8), boff = lds_byte(wc * 32 + fr, fq * 8);
;     ...
;     f32x4 acc[2][2][4][2];
; #pragma unroll
;     for (int a = 0; a < 2; ++a)
; #pragma unroll
;         for (int b = 0; b < 2; ++b)
; #pragma unroll
;             for (int m = 0; m < 4; ++m)
; #pragma unroll
;                 for (int n = 0; n < 2; ++n) acc[a][b][m][n] = (f32x4){0.f, 0.f, 0.f, 0.f};
;     bf16x8 At[4][2], B0[2][2], B1[2][2];
;     const char* cA = (const char*)g.A + (size_t)cur.pm * tstep; const char* cB = (const char*)g.Bt + (size_t)cur.pn * tstep;
;     PG8_STAGE(PG8_SB(0, 0), cB, voffB); PG8_STAGE(PG8_SA(0, 0), cA, voffA); PG8_STAGE(PG8_SB(0, 1), cB + hstep, voffB); PG8_STAGE(PG8_SA(0, 1), cA + hstep, voffA);
;     if (wr == 1) PG8_BAR;
;     PG8_WAIT_V(4); PG8_BAR;
;     PG8_STAGE(PG8_SB(1, 0), cB + kstep, voffB); PG8_STAGE(PG8_SA(1, 0), cA + kstep, voffA); PG8_STAGE(PG8_SB(1, 1), cB + hstep + kstep, voffB);
;     PG8_WAIT_V(6); PG8_BAR;
.LBB0_323:
	v_lshl_add_u64 v[8:9], s[10:11], 0, v[0:1]
	v_mov_b32_e32 v131, v1
	v_lshl_add_u64 v[10:11], s[10:11], 0, v[130:131]
	s_add_i32 m0, s47, 0x18000
	v_lshl_add_u64 v[8:9], v[8:9], 0, s[76:77]
	v_lshl_add_u64 v[12:13], s[12:13], 0, v[0:1]
	s_waitcnt vmcnt(4)
	s_barrier
	global_load_lds_dwordx4 v[8:9], off
	v_lshl_add_u64 v[8:9], v[10:11], 0, s[76:77]
	s_add_i32 m0, s47, 0x1a000
	s_add_i32 s53, s47, 0x8000
	v_lshl_add_u64 v[14:15], s[12:13], 0, v[130:131]
	global_load_lds_dwordx4 v[8:9], off
	v_lshl_add_u64 v[8:9], v[12:13], 0, s[76:77]
	s_mov_b32 m0, s53
	s_add_i32 s54, s47, 0xa000
	v_lshl_add_u64 v[16:17], s[4:5], 0, v[0:1]
	global_load_lds_dwordx4 v[8:9], off
	v_lshl_add_u64 v[8:9], v[14:15], 0, s[76:77]
	s_mov_b32 m0, s54
	v_lshl_add_u64 v[18:19], s[4:5], 0, v[130:131]
	global_load_lds_dwordx4 v[8:9], off
	s_add_i32 m0, s47, 0x1c000
	v_lshl_add_u64 v[8:9], v[16:17], 0, s[76:77]
	global_load_lds_dwordx4 v[8:9], off
	v_lshl_add_u64 v[8:9], v[18:19], 0, s[76:77]
	s_add_i32 m0, s47, 0x1e000
	v_lshrrev_b32_e32 v21, 1, v50
	global_load_lds_dwordx4 v[8:9], off
	v_and_b32_e32 v21, 24, v21
	v_and_b32_e32 v20, 15, v50
	v_lshlrev_b32_e32 v22, 1, v21
	v_lshl_or_b32 v140, s22, 6, v20
	v_lshl_or_b32 v22, v20, 6, v22
	v_lshlrev_b32_e32 v20, 2, v20
	s_lshl_b32 s2, s2, 5
	s_lshl_b32 s4, s22, 13
	v_and_b32_e32 v23, 32, v20
	s_and_b32 s2, s2, 0x60
	v_bitop3_b32 v24, v22, s4, v23 bitop3:0xde
	s_lshl_b32 s4, s2, 7
	v_cvt_u32_f32_e32 v8, v51
	v_bitop3_b32 v141, v22, s4, v23 bitop3:0xde
	s_lshl_b32 s4, s22, 8
	s_add_i32 s4, s4, 0
	s_add_i32 s4, s4, 0x20000
	v_add_u32_e32 v142, s4, v20
	v_or_b32_e32 v143, s2, v21
	s_sub_i32 s2, 0, s14
	v_readfirstlane_b32 s4, v8
	s_mul_i32 s2, s2, s4
	s_lshr_b32 s16, s16, 6
	s_mul_hi_u32 s2, s4, s2
	s_add_i32 s55, s16, -2
	s_add_i32 s56, s4, s2
	s_add_u32 s4, s21, 0x80
	v_add_u32_e32 v2, v4, v2
	s_addc_u32 s5, 0, 0
	v_add_lshl_u32 v2, v2, v3, 1
	v_mov_b32_e32 v3, v1
	v_lshl_add_u64 v[132:133], s[4:5], 0, v[0:1]
	v_add_u32_e32 v2, v7, v5
	s_waitcnt vmcnt(6)
	v_add_lshl_u32 v2, v2, v6, 1
	v_lshl_add_u64 v[134:135], s[4:5], 0, v[130:131]
	v_mov_b32_e32 v2, 0
	s_mov_b32 s57, 0
	v_add_u32_e32 v144, 0, v24
	v_and_b32_e32 v249, 15, v50
	v_lshrrev_b32_e32 v250, 1, v249
	v_bfe_u32 v251, v50, 4, 2
	v_xor_b32_e32 v250, v250, v251
	v_lshlrev_b32_e32 v250, 4, v250
	v_lshl_or_b32 v250, v249, 7, v250
	v_lshrrev_b32_e32 v249, 8, v50
	v_lshl_or_b32 v144, v249, 13, v250
	v_bfe_u32 v249, v50, 6, 2
	v_lshl_or_b32 v141, v249, 12, v250
	v_xor_b32_e32 v249, 64, v144
	v_xor_b32_e32 v251, 64, v141
	v_mov_b32_e32 v3, v2
	v_mov_b32_e32 v4, v2
	v_mov_b32_e32 v5, v2
	v_mov_b32_e32 v6, v2
	v_mov_b32_e32 v7, v2
	v_mov_b32_e32 v8, v2
	v_mov_b32_e32 v9, v2
	v_mov_b32_e32 v10, v2
	v_mov_b32_e32 v11, v2
	v_mov_b32_e32 v12, v2
	v_mov_b32_e32 v13, v2
	v_mov_b32_e32 v14, v2
	v_mov_b32_e32 v15, v2
	v_mov_b32_e32 v16, v2
	v_mov_b32_e32 v17, v2
	v_mov_b32_e32 v18, v2
	v_mov_b32_e32 v19, v2
	v_mov_b32_e32 v20, v2
	v_mov_b32_e32 v21, v2
	v_mov_b32_e32 v22, v2
	v_mov_b32_e32 v23, v2
	v_mov_b32_e32 v24, v2
	v_mov_b32_e32 v25, v2
	v_mov_b32_e32 v26, v2
	v_mov_b32_e32 v27, v2
	v_mov_b32_e32 v28, v2
	v_mov_b32_e32 v29, v2
	v_mov_b32_e32 v30, v2
	v_mov_b32_e32 v31, v2
	v_mov_b32_e32 v32, v2
	v_mov_b32_e32 v33, v2
	v_mov_b32_e32 v34, v2
	v_mov_b32_e32 v35, v2
	v_mov_b32_e32 v36, v2
	v_mov_b32_e32 v37, v2
	v_mov_b32_e32 v38, v2
	v_mov_b32_e32 v39, v2
	v_mov_b32_e32 v40, v2
	v_mov_b32_e32 v41, v2
	v_mov_b32_e32 v42, v2
	v_mov_b32_e32 v43, v2
	v_mov_b32_e32 v44, v2
	v_mov_b32_e32 v45, v2
	v_mov_b32_e32 v46, v2
	v_mov_b32_e32 v47, v2
	v_mov_b32_e32 v48, v2
	v_mov_b32_e32 v49, v2
	v_mov_b32_e32 v50, v2
	v_mov_b32_e32 v51, v2
	v_mov_b32_e32 v52, v2
	v_mov_b32_e32 v53, v2
	v_mov_b32_e32 v54, v2
	v_mov_b32_e32 v55, v2
	v_mov_b32_e32 v56, v2
	v_mov_b32_e32 v57, v2
	v_mov_b32_e32 v58, v2
	v_mov_b32_e32 v59, v2
	v_mov_b32_e32 v60, v2
	v_mov_b32_e32 v61, v2
	v_mov_b32_e32 v62, v2
	v_mov_b32_e32 v63, v2
	v_mov_b32_e32 v64, v2
	v_mov_b32_e32 v65, v2
	v_mov_b32_e32 v66, v2
	v_mov_b32_e32 v67, v2
	v_mov_b32_e32 v68, v2
	v_mov_b32_e32 v69, v2
	v_mov_b32_e32 v70, v2
	v_mov_b32_e32 v71, v2
	v_mov_b32_e32 v72, v2
	v_mov_b32_e32 v73, v2
	v_mov_b32_e32 v74, v2
	v_mov_b32_e32 v75, v2
	v_mov_b32_e32 v76, v2
	v_mov_b32_e32 v77, v2
	v_mov_b32_e32 v78, v2
	v_mov_b32_e32 v79, v2
	v_mov_b32_e32 v80, v2
	v_mov_b32_e32 v81, v2
	v_mov_b32_e32 v82, v2
	v_mov_b32_e32 v83, v2
	v_mov_b32_e32 v84, v2
	v_mov_b32_e32 v85, v2
	v_mov_b32_e32 v86, v2
	v_mov_b32_e32 v87, v2
	v_mov_b32_e32 v88, v2
	v_mov_b32_e32 v89, v2
	v_mov_b32_e32 v90, v2
	v_mov_b32_e32 v91, v2
	v_mov_b32_e32 v92, v2
	v_mov_b32_e32 v93, v2
	v_mov_b32_e32 v94, v2
	v_mov_b32_e32 v95, v2
	v_mov_b32_e32 v96, v2
	v_mov_b32_e32 v97, v2
	v_mov_b32_e32 v98, v2
	v_mov_b32_e32 v99, v2
	v_mov_b32_e32 v100, v2
	v_mov_b32_e32 v101, v2
	v_mov_b32_e32 v102, v2
	v_mov_b32_e32 v103, v2
	v_mov_b32_e32 v104, v2
	v_mov_b32_e32 v105, v2
	v_mov_b32_e32 v106, v2
	v_mov_b32_e32 v107, v2
	v_mov_b32_e32 v108, v2
	v_mov_b32_e32 v109, v2
	v_mov_b32_e32 v110, v2
	v_mov_b32_e32 v111, v2
	v_mov_b32_e32 v112, v2
	v_mov_b32_e32 v113, v2
	v_mov_b32_e32 v114, v2
	v_mov_b32_e32 v115, v2
	v_mov_b32_e32 v116, v2
	v_mov_b32_e32 v117, v2
	v_mov_b32_e32 v118, v2
	v_mov_b32_e32 v119, v2
	v_mov_b32_e32 v120, v2
	v_mov_b32_e32 v121, v2
	v_mov_b32_e32 v122, v2
	v_mov_b32_e32 v123, v2
	v_mov_b32_e32 v124, v2
	v_mov_b32_e32 v125, v2
	v_mov_b32_e32 v126, v2
	v_mov_b32_e32 v127, v2
	v_mov_b32_e32 v128, v2
	v_mov_b32_e32 v129, v2
	s_barrier
	s_branch .LBB0_325

; #define PG8_STAGE(bufoff, gbase, voff) do { _Pragma("unroll") for (int _i = 0; _i < 2; ++_i) \
;         __builtin_amdgcn_global_load_lds((const unsigned*)((const char*)(gbase) + (voff)[_i]), (LAS unsigned*)(lds + (bufoff) + ldsw + _i * 8192), 16, 0, 0); } while (0)
; #define PG8_LDA(dst, b, h) do { _Pragma("unroll") for (int m = 0; m < 4; ++m) _Pragma("unroll") for (int k = 0; k < 2; ++k) dst[m][k] = *(const LAS bf16x8*)(lds + PG8_SA(b, h) + aoff + m * 2048 + k * 1024); } while (0)
; #define PG8_LDB(dst, b, h) do { _Pragma("unroll") for (int n = 0; n < 2; ++n) _Pragma("unroll") for (int k = 0; k < 2; ++k) dst[n][k] = *(const LAS bf16x8*)(lds + PG8_SB(b, h) + boff + n * 2048 + k * 1024); } while (0)
; #define PG8_MMA(ai, bj, At, Bt) do { __builtin_amdgcn_s_setprio(1); _Pragma("unroll") for (int m = 0; m < 4; ++m) _Pragma("unroll") for (int n = 0; n < 2; ++n) _Pragma("unroll") for (int k = 0; k < 2; ++k) \
;         acc[ai][bj][m][n] = __builtin_amdgcn_mfma_f32_16x16x32_bf16(Bt[n][k], At[m][k], acc[ai][bj][m][n], 0, 0, 0); __builtin_amdgcn_s_setprio(0); } while (0)
; #define PG8_WAIT_L(n) asm volatile("s_waitcnt lgkmcnt(" #n ")" ::: "memory")
; template <int MODE, class EpiT, class Sched>
; __device__ __forceinline__ void gemm_phase(LAS unsigned char* lds, const Gemm g, const Sched& S, const EpiT& E) {
;     ...
;         const bool has_next = S.next(ui + 1, nxt);
;         const char* nA = has_next ? (const char*)g.A + (size_t)nxt.pm * tstep : cA; const char* nB = has_next ? (const char*)g.Bt + (size_t)nxt.pn * tstep : cB;
;         for (int t = 0; t < nt; t += 2) {
;             const bool last = (t == nt - 2);
;             const char* a1 = cA + (size_t)(t + 1) * kstep;
;             const char* a2 = last ? nA : cA + (size_t)(t + 2) * kstep; const char* b2 = last ? nB : cB + (size_t)(t + 2) * kstep;
;             const char* a3 = a2 + kstep; const char* b3 = b2 + kstep;
;             PG8_LDB(B0, 0, 0); PG8_SCHED; PG8_LDA(At, 0, 0); PG8_STAGE(PG8_SA(1, 1), a1 + hstep, voffA);
;             PG8_WAIT_L(8); PG8_BAR; PG8_WAIT_L(0); PG8_MMA(0, 0, At, B0); PG8_BAR; PG8_SCHED;
;             PG8_LDB(B1, 0, 1); PG8_STAGE(PG8_SB(0, 0), b2, voffB);
;             PG8_BAR; PG8_WAIT_L(0); PG8_MMA(0, 1, At, B1); PG8_BAR;
;             PG8_LDA(At, 0, 1); PG8_STAGE(PG8_SA(0, 0), a2, voffA);
;             PG8_BAR; PG8_WAIT_L(0); PG8_MMA(1, 0, At, B0); PG8_BAR; PG8_SCHED;
.LBB0_332:
	s_add_i32 s23, s22, 2
	s_add_u32 s30, s12, s4
	s_addc_u32 s38, s13, s5
	s_add_u32 s44, s10, s4
	s_addc_u32 s45, s11, s5
	s_add_i32 s58, 0, 0x10000
	v_add_u32_e32 v145, s58, v141
	v_add_u32_e32 v250, s58, v251
	ds_read_b128 v[146:149], v145
	ds_read_b128 v[150:153], v250
	ds_read_b128 v[154:157], v145 offset:2048
	ds_read_b128 v[158:161], v250 offset:2048
	s_cmp_eq_u32 s55, s22
	s_cselect_b32 s39, s29, s38
	s_cselect_b32 s38, s28, s30
	s_cselect_b32 s45, s35, s45
	s_cselect_b32 s44, s34, s44
	v_lshl_add_u64 v[198:199], s[12:13], 0, v[138:139]
	s_add_i32 m0, s47, 0xc000
	ds_read_b128 v[162:165], v144
	ds_read_b128 v[166:169], v249
	ds_read_b128 v[170:173], v144 offset:2048
	ds_read_b128 v[174:177], v249 offset:2048
	ds_read_b128 v[182:185], v144 offset:4096
	ds_read_b128 v[186:189], v249 offset:4096
	ds_read_b128 v[190:193], v144 offset:6144
	ds_read_b128 v[194:197], v249 offset:6144
	global_load_lds_dwordx4 v[198:199], off
	v_lshl_add_u64 v[198:199], s[12:13], 0, v[136:137]
	s_add_i32 m0, s47, 0xe000
	s_nop 0
	global_load_lds_dwordx4 v[198:199], off
	s_waitcnt lgkmcnt(8)
	s_barrier
	s_waitcnt lgkmcnt(0)
	v_mfma_f32_16x16x32_bf16 v[126:129], v[146:149], v[162:165], v[126:129]
	v_mfma_f32_16x16x32_bf16 v[122:125], v[154:157], v[162:165], v[122:125]
	v_mfma_f32_16x16x32_bf16 v[118:121], v[146:149], v[170:173], v[118:121]
	v_mfma_f32_16x16x32_bf16 v[114:117], v[154:157], v[170:173], v[114:117]
	v_mfma_f32_16x16x32_bf16 v[110:113], v[146:149], v[182:185], v[110:113]
	v_mfma_f32_16x16x32_bf16 v[106:109], v[154:157], v[182:185], v[106:109]
	v_mfma_f32_16x16x32_bf16 v[102:105], v[146:149], v[190:193], v[102:105]
	v_mfma_f32_16x16x32_bf16 v[98:101], v[154:157], v[190:193], v[98:101]
	v_mfma_f32_16x16x32_bf16 v[126:129], v[150:153], v[166:169], v[126:129]
	v_mfma_f32_16x16x32_bf16 v[122:125], v[158:161], v[166:169], v[122:125]
	v_mfma_f32_16x16x32_bf16 v[118:121], v[150:153], v[174:177], v[118:121]
	v_mfma_f32_16x16x32_bf16 v[114:117], v[158:161], v[174:177], v[114:117]
	v_mfma_f32_16x16x32_bf16 v[110:113], v[150:153], v[186:189], v[110:113]
	v_mfma_f32_16x16x32_bf16 v[106:109], v[158:161], v[186:189], v[106:109]
	v_mfma_f32_16x16x32_bf16 v[102:105], v[150:153], v[194:197], v[102:105]
	v_mfma_f32_16x16x32_bf16 v[98:101], v[158:161], v[194:197], v[98:101]
	s_barrier
	s_add_i32 s22, 0, 0x14000
	s_add_i32 s30, s58, s46
	v_add_u32_e32 v145, s22, v141
	v_add_u32_e32 v250, s22, v251
	v_lshl_add_u64 v[198:199], s[44:45], 0, v[0:1]
	s_mov_b32 m0, s30
	ds_read_b128 v[220:223], v145
	ds_read_b128 v[224:227], v250
	ds_read_b128 v[228:231], v145 offset:2048
	ds_read_b128 v[232:235], v250 offset:2048
	global_load_lds_dwordx4 v[198:199], off
	v_lshl_add_u64 v[236:237], s[44:45], 0, v[130:131]
	s_add_i32 m0, s30, 0x2000
	s_nop 0
	global_load_lds_dwordx4 v[236:237], off
	s_barrier
	s_waitcnt lgkmcnt(0)
	v_mfma_f32_16x16x32_bf16 v[94:97], v[220:223], v[162:165], v[94:97]
	v_mfma_f32_16x16x32_bf16 v[90:93], v[228:231], v[162:165], v[90:93]
	v_mfma_f32_16x16x32_bf16 v[86:89], v[220:223], v[170:173], v[86:89]
	v_mfma_f32_16x16x32_bf16 v[82:85], v[228:231], v[170:173], v[82:85]
	v_mfma_f32_16x16x32_bf16 v[78:81], v[220:223], v[182:185], v[78:81]
	v_mfma_f32_16x16x32_bf16 v[74:77], v[228:231], v[182:185], v[74:77]
	v_mfma_f32_16x16x32_bf16 v[70:73], v[220:223], v[190:193], v[70:73]
	v_mfma_f32_16x16x32_bf16 v[66:69], v[228:231], v[190:193], v[66:69]
	v_mfma_f32_16x16x32_bf16 v[94:97], v[224:227], v[166:169], v[94:97]
	v_mfma_f32_16x16x32_bf16 v[90:93], v[232:235], v[166:169], v[90:93]
	v_mfma_f32_16x16x32_bf16 v[86:89], v[224:227], v[174:177], v[86:89]
	v_mfma_f32_16x16x32_bf16 v[82:85], v[232:235], v[174:177], v[82:85]
	v_mfma_f32_16x16x32_bf16 v[78:81], v[224:227], v[186:189], v[78:81]
	v_mfma_f32_16x16x32_bf16 v[74:77], v[232:235], v[186:189], v[74:77]
	v_mfma_f32_16x16x32_bf16 v[70:73], v[224:227], v[194:197], v[70:73]
	v_mfma_f32_16x16x32_bf16 v[66:69], v[232:235], v[194:197], v[66:69]
	s_barrier
	s_mov_b32 m0, s47
	v_lshl_add_u64 v[238:239], s[38:39], 0, v[0:1]
	ds_read_b128 v[162:165], v144 offset:16384
	ds_read_b128 v[166:169], v249 offset:16384
	ds_read_b128 v[170:173], v144 offset:18432
	ds_read_b128 v[174:177], v249 offset:18432
	ds_read_b128 v[182:185], v144 offset:20480
	ds_read_b128 v[186:189], v249 offset:20480
	ds_read_b128 v[190:193], v144 offset:22528
	ds_read_b128 v[194:197], v249 offset:22528
	global_load_lds_dwordx4 v[238:239], off
	v_lshl_add_u64 v[240:241], s[38:39], 0, v[130:131]
	s_mov_b32 m0, s50
	s_nop 0
	global_load_lds_dwordx4 v[240:241], off
	s_barrier
	s_waitcnt lgkmcnt(0)
	v_mfma_f32_16x16x32_bf16 v[62:65], v[146:149], v[162:165], v[62:65]
	v_mfma_f32_16x16x32_bf16 v[58:61], v[154:157], v[162:165], v[58:61]
	v_mfma_f32_16x16x32_bf16 v[54:57], v[146:149], v[170:173], v[54:57]
	v_mfma_f32_16x16x32_bf16 v[50:53], v[154:157], v[170:173], v[50:53]
	v_mfma_f32_16x16x32_bf16 v[46:49], v[146:149], v[182:185], v[46:49]
	v_mfma_f32_16x16x32_bf16 v[42:45], v[154:157], v[182:185], v[42:45]
	v_mfma_f32_16x16x32_bf16 v[38:41], v[146:149], v[190:193], v[38:41]
	v_mfma_f32_16x16x32_bf16 v[34:37], v[154:157], v[190:193], v[34:37]
	v_mfma_f32_16x16x32_bf16 v[62:65], v[150:153], v[166:169], v[62:65]
	v_mfma_f32_16x16x32_bf16 v[58:61], v[158:161], v[166:169], v[58:61]
	v_mfma_f32_16x16x32_bf16 v[54:57], v[150:153], v[174:177], v[54:57]
	v_mfma_f32_16x16x32_bf16 v[50:53], v[158:161], v[174:177], v[50:53]
	v_mfma_f32_16x16x32_bf16 v[46:49], v[150:153], v[186:189], v[46:49]
	v_mfma_f32_16x16x32_bf16 v[42:45], v[158:161], v[186:189], v[42:45]
	v_mfma_f32_16x16x32_bf16 v[38:41], v[150:153], v[194:197], v[38:41]
	v_mfma_f32_16x16x32_bf16 v[34:37], v[158:161], v[194:197], v[34:37]
	s_barrier
; #define PG8_STAGE(bufoff, gbase, voff) do { _Pragma("unroll") for (int _i = 0; _i < 2; ++_i) \
;         __builtin_amdgcn_global_load_lds((const unsigned*)((const char*)(gbase) + (voff)[_i]), (LAS unsigned*)(lds + (bufoff) + ldsw + _i * 8192), 16, 0, 0); } while (0)
; #define PG8_LDA(dst, b, h) do { _Pragma("unroll") for (int m = 0; m < 4; ++m) _Pragma("unroll") for (int k = 0; k < 2; ++k) dst[m][k] = *(const LAS bf16x8*)(lds + PG8_SA(b, h) + aoff + m * 2048 + k * 1024); } while (0)
; #define PG8_LDB(dst, b, h) do { _Pragma("unroll") for (int n = 0; n < 2; ++n) _Pragma("unroll") for (int k = 0; k < 2; ++k) dst[n][k] = *(const LAS bf16x8*)(lds + PG8_SB(b, h) + boff + n * 2048 + k * 1024); } while (0)
; #define PG8_MMA(ai, bj, At, Bt) do { __builtin_amdgcn_s_setprio(1); _Pragma("unroll") for (int m = 0; m < 4; ++m) _Pragma("unroll") for (int n = 0; n < 2; ++n) _Pragma("unroll") for (int k = 0; k < 2; ++k) \
;         acc[ai][bj][m][n] = __builtin_amdgcn_mfma_f32_16x16x32_bf16(Bt[n][k], At[m][k], acc[ai][bj][m][n], 0, 0, 0); __builtin_amdgcn_s_setprio(0); } while (0)
; #define PG8_WAIT_V(n) asm volatile("s_waitcnt vmcnt(" #n ")" ::: "memory")
; #define PG8_WAIT_L(n) asm volatile("s_waitcnt lgkmcnt(" #n ")" ::: "memory")
; #define PG8_BAR __builtin_amdgcn_s_barrier()
; #define PG8_SCHED __builtin_amdgcn_sched_barrier(0)
; template <int MODE, class EpiT, class Sched>
; __device__ __forceinline__ void gemm_phase(LAS unsigned char* lds, const Gemm g, const Sched& S, const EpiT& E) {
;     ...
;             PG8_STAGE(PG8_SB(0, 1), b2 + hstep, voffB);
;             PG8_WAIT_V(6); PG8_BAR; PG8_MMA(1, 1, At, B1); PG8_BAR;
;             PG8_LDB(B0, 1, 0); PG8_SCHED; PG8_LDA(At, 1, 0); PG8_STAGE(PG8_SA(0, 1), a2 + hstep, voffA);
;             PG8_WAIT_L(8); PG8_BAR; PG8_WAIT_L(0); PG8_MMA(0, 0, At, B0); PG8_BAR; PG8_SCHED;
;             PG8_LDB(B1, 1, 1); PG8_STAGE(PG8_SB(1, 0), b3, voffB);
;             PG8_BAR; PG8_WAIT_L(0); PG8_MMA(0, 1, At, B1); PG8_BAR;
;             PG8_LDA(At, 1, 1); PG8_STAGE(PG8_SA(1, 0), a3, voffA);
;             PG8_BAR; PG8_WAIT_L(0); PG8_MMA(1, 0, At, B0); PG8_BAR; PG8_SCHED;
	s_add_u32 s44, s44, s21
	s_addc_u32 s45, s45, 0
	s_add_i32 s22, s22, s46
	v_lshl_add_u64 v[242:243], s[44:45], 0, v[0:1]
	s_mov_b32 m0, s22
	v_lshl_add_u64 v[244:245], s[44:45], 0, v[130:131]
	global_load_lds_dwordx4 v[242:243], off
	s_add_i32 m0, s22, 0x2000
	s_nop 0
	global_load_lds_dwordx4 v[244:245], off
	s_waitcnt vmcnt(6)
	s_barrier
	v_mfma_f32_16x16x32_bf16 v[30:33], v[220:223], v[162:165], v[30:33]
	v_mfma_f32_16x16x32_bf16 v[26:29], v[228:231], v[162:165], v[26:29]
	v_mfma_f32_16x16x32_bf16 v[22:25], v[220:223], v[170:173], v[22:25]
	v_mfma_f32_16x16x32_bf16 v[18:21], v[228:231], v[170:173], v[18:21]
	v_mfma_f32_16x16x32_bf16 v[14:17], v[220:223], v[182:185], v[14:17]
	v_mfma_f32_16x16x32_bf16 v[10:13], v[228:231], v[182:185], v[10:13]
	v_mfma_f32_16x16x32_bf16 v[6:9], v[220:223], v[190:193], v[6:9]
	v_mfma_f32_16x16x32_bf16 v[2:5], v[228:231], v[190:193], v[2:5]
	v_mfma_f32_16x16x32_bf16 v[30:33], v[224:227], v[166:169], v[30:33]
	v_mfma_f32_16x16x32_bf16 v[26:29], v[232:235], v[166:169], v[26:29]
	v_mfma_f32_16x16x32_bf16 v[22:25], v[224:227], v[174:177], v[22:25]
	v_mfma_f32_16x16x32_bf16 v[18:21], v[232:235], v[174:177], v[18:21]
	v_mfma_f32_16x16x32_bf16 v[14:17], v[224:227], v[186:189], v[14:17]
	v_mfma_f32_16x16x32_bf16 v[10:13], v[232:235], v[186:189], v[10:13]
	v_mfma_f32_16x16x32_bf16 v[6:9], v[224:227], v[194:197], v[6:9]
	v_mfma_f32_16x16x32_bf16 v[2:5], v[232:235], v[194:197], v[2:5]
	s_barrier
	s_add_i32 s22, 0, 0x18000
	v_add_u32_e32 v145, s22, v141
	v_add_u32_e32 v250, s22, v251
	ds_read_b128 v[146:149], v145
	ds_read_b128 v[150:153], v250
	ds_read_b128 v[154:157], v145 offset:2048
	ds_read_b128 v[158:161], v250 offset:2048
	s_add_u32 s38, s38, s21
	s_addc_u32 s39, s39, 0
	s_mov_b32 m0, s51
	v_lshl_add_u64 v[220:221], s[38:39], 0, v[0:1]
	ds_read_b128 v[162:165], v144 offset:32768
	ds_read_b128 v[166:169], v249 offset:32768
	ds_read_b128 v[170:173], v144 offset:34816
	ds_read_b128 v[174:177], v249 offset:34816
	ds_read_b128 v[182:185], v144 offset:36864
	ds_read_b128 v[186:189], v249 offset:36864
	ds_read_b128 v[190:193], v144 offset:38912
	ds_read_b128 v[194:197], v249 offset:38912
	global_load_lds_dwordx4 v[220:221], off
	v_lshl_add_u64 v[220:221], s[38:39], 0, v[130:131]
	s_mov_b32 m0, s52
	s_nop 0
	global_load_lds_dwordx4 v[220:221], off
	s_waitcnt lgkmcnt(8)
	s_barrier
	s_waitcnt lgkmcnt(0)
	v_mfma_f32_16x16x32_bf16 v[126:129], v[146:149], v[162:165], v[126:129]
	v_mfma_f32_16x16x32_bf16 v[122:125], v[154:157], v[162:165], v[122:125]
	v_mfma_f32_16x16x32_bf16 v[118:121], v[146:149], v[170:173], v[118:121]
	v_mfma_f32_16x16x32_bf16 v[114:117], v[154:157], v[170:173], v[114:117]
	v_mfma_f32_16x16x32_bf16 v[110:113], v[146:149], v[182:185], v[110:113]
	v_mfma_f32_16x16x32_bf16 v[106:109], v[154:157], v[182:185], v[106:109]
	v_mfma_f32_16x16x32_bf16 v[102:105], v[146:149], v[190:193], v[102:105]
	v_mfma_f32_16x16x32_bf16 v[98:101], v[154:157], v[190:193], v[98:101]
	v_mfma_f32_16x16x32_bf16 v[126:129], v[150:153], v[166:169], v[126:129]
	v_mfma_f32_16x16x32_bf16 v[122:125], v[158:161], v[166:169], v[122:125]
	v_mfma_f32_16x16x32_bf16 v[118:121], v[150:153], v[174:177], v[118:121]
	v_mfma_f32_16x16x32_bf16 v[114:117], v[158:161], v[174:177], v[114:117]
	v_mfma_f32_16x16x32_bf16 v[110:113], v[150:153], v[186:189], v[110:113]
	v_mfma_f32_16x16x32_bf16 v[106:109], v[158:161], v[186:189], v[106:109]
	v_mfma_f32_16x16x32_bf16 v[102:105], v[150:153], v[194:197], v[102:105]
	v_mfma_f32_16x16x32_bf16 v[98:101], v[158:161], v[194:197], v[98:101]
	s_barrier
	s_add_i32 s30, 0, 0x1c000
	s_add_i32 s22, s22, s46
	v_add_u32_e32 v145, s30, v141
	v_add_u32_e32 v250, s30, v251
	v_lshl_add_u64 v[198:199], v[198:199], 0, s[76:77]
	s_mov_b32 m0, s22
	ds_read_b128 v[220:223], v145
	ds_read_b128 v[224:227], v250
	ds_read_b128 v[228:231], v145 offset:2048
	ds_read_b128 v[232:235], v250 offset:2048
	global_load_lds_dwordx4 v[198:199], off
	v_lshl_add_u64 v[198:199], v[236:237], 0, s[76:77]
	s_add_i32 m0, s22, 0x2000
	s_nop 0
	global_load_lds_dwordx4 v[198:199], off
	s_barrier
	s_waitcnt lgkmcnt(0)
	v_mfma_f32_16x16x32_bf16 v[94:97], v[220:223], v[162:165], v[94:97]
	v_mfma_f32_16x16x32_bf16 v[90:93], v[228:231], v[162:165], v[90:93]
	v_mfma_f32_16x16x32_bf16 v[86:89], v[220:223], v[170:173], v[86:89]
	v_mfma_f32_16x16x32_bf16 v[82:85], v[228:231], v[170:173], v[82:85]
	v_mfma_f32_16x16x32_bf16 v[78:81], v[220:223], v[182:185], v[78:81]
	v_mfma_f32_16x16x32_bf16 v[74:77], v[228:231], v[182:185], v[74:77]
	v_mfma_f32_16x16x32_bf16 v[70:73], v[220:223], v[190:193], v[70:73]
	v_mfma_f32_16x16x32_bf16 v[66:69], v[228:231], v[190:193], v[66:69]
	v_mfma_f32_16x16x32_bf16 v[94:97], v[224:227], v[166:169], v[94:97]
	v_mfma_f32_16x16x32_bf16 v[90:93], v[232:235], v[166:169], v[90:93]
	v_mfma_f32_16x16x32_bf16 v[86:89], v[224:227], v[174:177], v[86:89]
	v_mfma_f32_16x16x32_bf16 v[82:85], v[232:235], v[174:177], v[82:85]
	v_mfma_f32_16x16x32_bf16 v[78:81], v[224:227], v[186:189], v[78:81]
	v_mfma_f32_16x16x32_bf16 v[74:77], v[232:235], v[186:189], v[74:77]
	v_mfma_f32_16x16x32_bf16 v[70:73], v[224:227], v[194:197], v[70:73]
	v_mfma_f32_16x16x32_bf16 v[66:69], v[232:235], v[194:197], v[66:69]
	s_barrier
	s_mov_b32 m0, s53
	v_lshl_add_u64 v[198:199], v[238:239], 0, s[76:77]
	ds_read_b128 v[162:165], v144 offset:49152
	ds_read_b128 v[166:169], v249 offset:49152
	ds_read_b128 v[170:173], v144 offset:51200
	ds_read_b128 v[174:177], v249 offset:51200
	ds_read_b128 v[182:185], v144 offset:53248
	ds_read_b128 v[186:189], v249 offset:53248
	ds_read_b128 v[190:193], v144 offset:55296
	ds_read_b128 v[194:197], v249 offset:55296
	global_load_lds_dwordx4 v[198:199], off
	v_lshl_add_u64 v[198:199], v[240:241], 0, s[76:77]
	s_mov_b32 m0, s54
	s_nop 0
	global_load_lds_dwordx4 v[198:199], off
	s_barrier
; __device__ __forceinline__ unsigned pk2(float lo, float hi) { unsigned r; asm volatile("v_cvt_pk_bf16_f32 %0, %1, %2" : "=v"(r) : "v"(lo), "v"(hi)); return r; }
; __device__ __forceinline__ float siluf_(float x) { return x * __builtin_amdgcn_rcpf(1.0f + __expf(-x)); }
; #define PG8_STAGE(bufoff, gbase, voff) do { _Pragma("unroll") for (int _i = 0; _i < 2; ++_i) \
;         __builtin_amdgcn_global_load_lds((const unsigned*)((const char*)(gbase) + (voff)[_i]), (LAS unsigned*)(lds + (bufoff) + ldsw + _i * 8192), 16, 0, 0); } while (0)
; #define PG8_MMA(ai, bj, At, Bt) do { __builtin_amdgcn_s_setprio(1); _Pragma("unroll") for (int m = 0; m < 4; ++m) _Pragma("unroll") for (int n = 0; n < 2; ++n) _Pragma("unroll") for (int k = 0; k < 2; ++k) \
;         acc[ai][bj][m][n] = __builtin_amdgcn_mfma_f32_16x16x32_bf16(Bt[n][k], At[m][k], acc[ai][bj][m][n], 0, 0, 0); __builtin_amdgcn_s_setprio(0); } while (0)
; #define PG8_BAR __builtin_amdgcn_s_barrier()
;     template <int mode> __device__ __forceinline__ void run(const f32x4 (&acc)[2][2][4][2], const Unit& u, int wr, int wc, int fr, int fq, const LAS float* sc) const {
;     ...
;         if (mode == 0) {
;             const int col0 = u.pn * HALF + wc * 32 + 8 * fq;
; #pragma unroll
;             for (int ai = 0; ai < 2; ++ai)
; #pragma unroll
;                 for (int m = 0; m < 4; ++m) {
;                     const int row = row0 + ai * HALF + m * 16;
;                     const float s = sc[ai * HALF + wr * 64 + m * 16 + fr];
;                     const f32x4 g0 = acc[ai][0][m][0] * s, u0 = acc[ai][1][m][0] * s, g1 = acc[ai][0][m][1] * s, u1 = acc[ai][1][m][1] * s;
;                     u32x4 w;
;                     w.x = pk2(siluf_(g0[0]) * u0[0], siluf_(g0[1]) * u0[1]); w.y = pk2(siluf_(g0[2]) * u0[2], siluf_(g0[3]) * u0[3]);
;                     w.z = pk2(siluf_(g1[0]) * u1[0], siluf_(g1[1]) * u1[1]); w.w = pk2(siluf_(g1[2]) * u1[2], siluf_(g1[3]) * u1[3]);
;                     *(u32x4*)(ob + (size_t)row * FF + col0) = w;
; template <int MODE, class EpiT, class Sched>
; __device__ __forceinline__ void gemm_phase(LAS unsigned char* lds, const Gemm g, const Sched& S, const EpiT& E) {
;     ...
;             PG8_BAR; PG8_WAIT_L(0); PG8_MMA(1, 0, At, B0); PG8_BAR; PG8_SCHED;
;             PG8_STAGE(PG8_SB(1, 1), b3 + hstep, voffB);
;             PG8_WAIT_V(6); PG8_BAR; PG8_MMA(1, 1, At, B1); PG8_BAR;
;         }
	s_waitcnt lgkmcnt(0)
	v_mfma_f32_16x16x32_bf16 v[62:65], v[146:149], v[162:165], v[62:65]
	v_mfma_f32_16x16x32_bf16 v[58:61], v[154:157], v[162:165], v[58:61]
	v_mfma_f32_16x16x32_bf16 v[54:57], v[146:149], v[170:173], v[54:57]
	v_mfma_f32_16x16x32_bf16 v[50:53], v[154:157], v[170:173], v[50:53]
	v_mfma_f32_16x16x32_bf16 v[46:49], v[146:149], v[182:185], v[46:49]
	v_mfma_f32_16x16x32_bf16 v[42:45], v[154:157], v[182:185], v[42:45]
	v_mfma_f32_16x16x32_bf16 v[38:41], v[146:149], v[190:193], v[38:41]
	v_mfma_f32_16x16x32_bf16 v[34:37], v[154:157], v[190:193], v[34:37]
	v_mfma_f32_16x16x32_bf16 v[62:65], v[150:153], v[166:169], v[62:65]
	v_mfma_f32_16x16x32_bf16 v[58:61], v[158:161], v[166:169], v[58:61]
	v_mfma_f32_16x16x32_bf16 v[54:57], v[150:153], v[174:177], v[54:57]
	v_mfma_f32_16x16x32_bf16 v[50:53], v[158:161], v[174:177], v[50:53]
	v_mfma_f32_16x16x32_bf16 v[46:49], v[150:153], v[186:189], v[46:49]
	v_mfma_f32_16x16x32_bf16 v[42:45], v[158:161], v[186:189], v[42:45]
	v_mfma_f32_16x16x32_bf16 v[38:41], v[150:153], v[194:197], v[38:41]
	v_mfma_f32_16x16x32_bf16 v[34:37], v[158:161], v[194:197], v[34:37]
	s_barrier
	s_add_i32 s22, s30, s46
	v_lshl_add_u64 v[146:147], v[242:243], 0, s[76:77]
	s_mov_b32 m0, s22
	s_nop 0
	global_load_lds_dwordx4 v[146:147], off
	v_lshl_add_u64 v[146:147], v[244:245], 0, s[76:77]
	s_add_i32 m0, s22, 0x2000
	s_nop 0
	global_load_lds_dwordx4 v[146:147], off
	s_waitcnt vmcnt(6)
	s_barrier
	v_mfma_f32_16x16x32_bf16 v[30:33], v[220:223], v[162:165], v[30:33]
	v_mfma_f32_16x16x32_bf16 v[26:29], v[228:231], v[162:165], v[26:29]
	v_mfma_f32_16x16x32_bf16 v[22:25], v[220:223], v[170:173], v[22:25]
	v_mfma_f32_16x16x32_bf16 v[18:21], v[228:231], v[170:173], v[18:21]
	v_mfma_f32_16x16x32_bf16 v[14:17], v[220:223], v[182:185], v[14:17]
	v_mfma_f32_16x16x32_bf16 v[10:13], v[228:231], v[182:185], v[10:13]
	v_mfma_f32_16x16x32_bf16 v[6:9], v[220:223], v[190:193], v[6:9]
	v_mfma_f32_16x16x32_bf16 v[2:5], v[228:231], v[190:193], v[2:5]
	v_mfma_f32_16x16x32_bf16 v[30:33], v[224:227], v[166:169], v[30:33]
	v_mfma_f32_16x16x32_bf16 v[26:29], v[232:235], v[166:169], v[26:29]
	v_mfma_f32_16x16x32_bf16 v[22:25], v[224:227], v[174:177], v[22:25]
	v_mfma_f32_16x16x32_bf16 v[18:21], v[232:235], v[174:177], v[18:21]
	v_mfma_f32_16x16x32_bf16 v[14:17], v[224:227], v[186:189], v[14:17]
	v_mfma_f32_16x16x32_bf16 v[10:13], v[232:235], v[186:189], v[10:13]
	v_mfma_f32_16x16x32_bf16 v[6:9], v[224:227], v[194:197], v[6:9]
	v_mfma_f32_16x16x32_bf16 v[2:5], v[232:235], v[194:197], v[2:5]
	s_barrier
	s_add_u32 s4, s4, 0x100
	s_addc_u32 s5, s5, 0
	v_lshl_add_u64 v[138:139], v[138:139], 0, s[80:81]
	v_lshl_add_u64 v[136:137], v[136:137], 0, s[80:81]
	s_cmp_ge_u32 s23, s16
	s_mov_b32 s22, s23
	s_cbranch_scc0 .LBB0_332
	v_lshl_add_u32 v145, s57, 10, v142
	ds_read_b32 v136, v145
	v_lshl_or_b32 v138, s8, 7, v143
	v_lshl_add_u32 v146, s9, 8, v140
	v_ashrrev_i32_e32 v139, 31, v138
	v_lshlrev_b64 v[138:139], 1, v[138:139]
	s_waitcnt lgkmcnt(0)
	v_pk_mul_f32 v[148:149], v[126:127], v[136:137] op_sel_hi:[1,0]
	v_pk_mul_f32 v[154:155], v[94:95], v[136:137] op_sel_hi:[1,0]
	v_mul_f32_e32 v147, 0xbfb8aa3b, v148
	v_exp_f32_e32 v147, v147
	v_pk_mul_f32 v[150:151], v[128:129], v[136:137] op_sel_hi:[1,0]
	v_pk_mul_f32 v[152:153], v[96:97], v[136:137] op_sel_hi:[1,0]
	v_pk_mul_f32 v[158:159], v[122:123], v[136:137] op_sel_hi:[1,0]
	v_add_f32_e32 v147, 1.0, v147
	v_rcp_f32_e32 v147, v147
	v_pk_mul_f32 v[156:157], v[124:125], v[136:137] op_sel_hi:[1,0]
	v_pk_mul_f32 v[160:161], v[92:93], v[136:137] op_sel_hi:[1,0]
	v_pk_mul_f32 v[136:137], v[90:91], v[136:137] op_sel_hi:[1,0]
	v_mul_f32_e32 v147, v148, v147
	v_mul_f32_e32 v148, 0xbfb8aa3b, v149
	v_exp_f32_e32 v148, v148
	v_mul_f32_e32 v147, v154, v147
	s_and_b64 vcc, exec, s[42:43]
	v_add_f32_e32 v148, 1.0, v148
	v_rcp_f32_e32 v148, v148
	s_nop 0
	v_mul_f32_e32 v148, v149, v148
	v_mul_f32_e32 v148, v155, v148
	v_cvt_pk_bf16_f32 v148, v147, v148
	v_mul_f32_e32 v147, 0xbfb8aa3b, v150
	v_mul_f32_e32 v149, 0xbfb8aa3b, v151
	v_exp_f32_e32 v147, v147
	v_exp_f32_e32 v149, v149
	v_add_f32_e32 v147, 1.0, v147
	v_add_f32_e32 v149, 1.0, v149
	v_rcp_f32_e32 v147, v147
	v_rcp_f32_e32 v149, v149
	v_mul_f32_e32 v147, v150, v147
	v_mul_f32_e32 v149, v151, v149
	v_mul_f32_e32 v147, v152, v147
	v_mul_f32_e32 v149, v153, v149
	v_cvt_pk_bf16_f32 v149, v147, v149
	v_mul_f32_e32 v147, 0xbfb8aa3b, v158
	v_exp_f32_e32 v147, v147
	s_nop 0
	v_add_f32_e32 v147, 1.0, v147
	v_rcp_f32_e32 v147, v147
	s_nop 0
	v_mul_f32_e32 v147, v158, v147
	v_mul_f32_e32 v136, v136, v147
	v_mul_f32_e32 v147, 0xbfb8aa3b, v159
	v_exp_f32_e32 v147, v147
	s_nop 0
	v_add_f32_e32 v147, 1.0, v147
	v_rcp_f32_e32 v147, v147
	s_nop 0
	v_mul_f32_e32 v147, v159, v147
	v_mul_f32_e32 v137, v137, v147
	v_cvt_pk_bf16_f32 v150, v136, v137
	v_mul_f32_e32 v136, 0xbfb8aa3b, v156
	v_mul_f32_e32 v137, 0xbfb8aa3b, v157
	v_exp_f32_e32 v136, v136
	v_exp_f32_e32 v137, v137
	v_or_b32_e32 v147, 16, v146
	v_add_f32_e32 v136, 1.0, v136
	v_add_f32_e32 v137, 1.0, v137
	v_rcp_f32_e32 v136, v136
	v_rcp_f32_e32 v137, v137
	v_mul_f32_e32 v136, v156, v136
	v_mul_f32_e32 v137, v157, v137
	v_mul_f32_e32 v136, v160, v136
	v_mul_f32_e32 v137, v161, v137
	v_cvt_pk_bf16_f32 v151, v136, v137
	v_mov_b64_e32 v[136:137], s[6:7]
	v_mad_i64_i32 v[152:153], s[4:5], v146, s33, v[136:137]
	v_lshl_add_u64 v[152:153], v[152:153], 0, v[138:139]
	global_store_dwordx4 v[152:153], v[148:151], off
	ds_read_b32 v148, v145 offset:64
	s_waitcnt lgkmcnt(0)
; __device__ __forceinline__ unsigned pk2(float lo, float hi) { unsigned r; asm volatile("v_cvt_pk_bf16_f32 %0, %1, %2" : "=v"(r) : "v"(lo), "v"(hi)); return r; }
; __device__ __forceinline__ float siluf_(float x) { return x * __builtin_amdgcn_rcpf(1.0f + __expf(-x)); }
;     template <int mode> __device__ __forceinline__ void run(const f32x4 (&acc)[2][2][4][2], const Unit& u, int wr, int wc, int fr, int fq, const LAS float* sc) const {
;     ...
;         if (mode == 0) {
;             const int col0 = u.pn * HALF + wc * 32 + 8 * fq;
; #pragma unroll
;             for (int ai = 0; ai < 2; ++ai)
; #pragma unroll
;                 for (int m = 0; m < 4; ++m) {
;                     const int row = row0 + ai * HALF + m * 16;
;                     const float s = sc[ai * HALF + wr * 64 + m * 16 + fr];
;                     const f32x4 g0 = acc[ai][0][m][0] * s, u0 = acc[ai][1][m][0] * s, g1 = acc[ai][0][m][1] * s, u1 = acc[ai][1][m][1] * s;
;                     u32x4 w;
;                     w.x = pk2(siluf_(g0[0]) * u0[0], siluf_(g0[1]) * u0[1]); w.y = pk2(siluf_(g0[2]) * u0[2], siluf_(g0[3]) * u0[3]);
;                     w.z = pk2(siluf_(g1[0]) * u1[0], siluf_(g1[1]) * u1[1]); w.w = pk2(siluf_(g1[2]) * u1[2], siluf_(g1[3]) * u1[3]);
;                     *(u32x4*)(ob + (size_t)row * FF + col0) = w;
;                 }
	v_pk_mul_f32 v[152:153], v[118:119], v[148:149] op_sel_hi:[1,0]
	v_pk_mul_f32 v[150:151], v[120:121], v[148:149] op_sel_hi:[1,0]
	v_pk_mul_f32 v[154:155], v[88:89], v[148:149] op_sel_hi:[1,0]
	v_pk_mul_f32 v[156:157], v[86:87], v[148:149] op_sel_hi:[1,0]
	v_pk_mul_f32 v[158:159], v[116:117], v[148:149] op_sel_hi:[1,0]
	v_pk_mul_f32 v[160:161], v[114:115], v[148:149] op_sel_hi:[1,0]
	v_pk_mul_f32 v[162:163], v[84:85], v[148:149] op_sel_hi:[1,0]
	v_pk_mul_f32 v[164:165], v[82:83], v[148:149] op_sel_hi:[1,0]
	v_mul_f32_e32 v148, 0xbfb8aa3b, v152
	v_mul_f32_e32 v149, 0xbfb8aa3b, v153
	v_exp_f32_e32 v148, v148
	v_exp_f32_e32 v149, v149
	v_add_f32_e32 v148, 1.0, v148
	v_add_f32_e32 v149, 1.0, v149
	v_rcp_f32_e32 v148, v148
	v_rcp_f32_e32 v149, v149
	v_mul_f32_e32 v148, v152, v148
	v_mul_f32_e32 v149, v153, v149
	v_mul_f32_e32 v148, v156, v148
	v_mul_f32_e32 v149, v157, v149
	v_cvt_pk_bf16_f32 v148, v148, v149
	v_mul_f32_e32 v149, 0xbfb8aa3b, v150
	v_exp_f32_e32 v149, v149
	v_mul_f32_e32 v152, 0xbfb8aa3b, v159
	v_exp_f32_e32 v152, v152
	v_add_f32_e32 v149, 1.0, v149
	v_rcp_f32_e32 v149, v149
	v_add_f32_e32 v152, 1.0, v152
	v_rcp_f32_e32 v152, v152
	v_mul_f32_e32 v149, v150, v149
	v_mul_f32_e32 v150, 0xbfb8aa3b, v151
	v_exp_f32_e32 v150, v150
	v_mul_f32_e32 v149, v154, v149
	v_mul_f32_e32 v152, v159, v152
	v_mul_f32_e32 v152, v163, v152
	v_add_f32_e32 v150, 1.0, v150
	v_rcp_f32_e32 v150, v150
	s_nop 0
	v_mul_f32_e32 v150, v151, v150
	v_mul_f32_e32 v150, v155, v150
	v_cvt_pk_bf16_f32 v149, v149, v150
	v_mul_f32_e32 v150, 0xbfb8aa3b, v160
	v_mul_f32_e32 v151, 0xbfb8aa3b, v161
	v_exp_f32_e32 v150, v150
	v_exp_f32_e32 v151, v151
	v_add_f32_e32 v150, 1.0, v150
	v_add_f32_e32 v151, 1.0, v151
	v_rcp_f32_e32 v150, v150
	v_rcp_f32_e32 v151, v151
	v_mul_f32_e32 v150, v160, v150
	v_mul_f32_e32 v151, v161, v151
	v_mul_f32_e32 v150, v164, v150
	v_mul_f32_e32 v151, v165, v151
	v_cvt_pk_bf16_f32 v150, v150, v151
	v_mul_f32_e32 v151, 0xbfb8aa3b, v158
	v_exp_f32_e32 v151, v151
	s_nop 0
	v_add_f32_e32 v151, 1.0, v151
	v_rcp_f32_e32 v151, v151
	s_nop 0
	v_mul_f32_e32 v151, v158, v151
	v_mul_f32_e32 v151, v162, v151
	v_cvt_pk_bf16_f32 v151, v151, v152
	v_mad_i64_i32 v[152:153], s[4:5], v147, s33, v[136:137]
	v_lshl_add_u64 v[152:153], v[152:153], 0, v[138:139]
	global_store_dwordx4 v[152:153], v[148:151], off
	ds_read_b32 v148, v145 offset:128
	v_or_b32_e32 v147, 32, v146
	s_waitcnt lgkmcnt(0)
	v_pk_mul_f32 v[152:153], v[110:111], v[148:149] op_sel_hi:[1,0]
	v_pk_mul_f32 v[150:151], v[112:113], v[148:149] op_sel_hi:[1,0]
	v_pk_mul_f32 v[154:155], v[80:81], v[148:149] op_sel_hi:[1,0]
	v_pk_mul_f32 v[156:157], v[78:79], v[148:149] op_sel_hi:[1,0]
	v_pk_mul_f32 v[158:159], v[108:109], v[148:149] op_sel_hi:[1,0]
	v_pk_mul_f32 v[160:161], v[106:107], v[148:149] op_sel_hi:[1,0]
	v_pk_mul_f32 v[162:163], v[76:77], v[148:149] op_sel_hi:[1,0]
	v_pk_mul_f32 v[164:165], v[74:75], v[148:149] op_sel_hi:[1,0]
	v_mul_f32_e32 v148, 0xbfb8aa3b, v152
	v_mul_f32_e32 v149, 0xbfb8aa3b, v153
	v_exp_f32_e32 v148, v148
	v_exp_f32_e32 v149, v149
	v_add_f32_e32 v148, 1.0, v148
	v_add_f32_e32 v149, 1.0, v149
	v_rcp_f32_e32 v148, v148
	v_rcp_f32_e32 v149, v149
	v_mul_f32_e32 v148, v152, v148
	v_mul_f32_e32 v149, v153, v149
	v_mul_f32_e32 v148, v156, v148
	v_mul_f32_e32 v149, v157, v149
	v_cvt_pk_bf16_f32 v148, v148, v149
	v_mul_f32_e32 v149, 0xbfb8aa3b, v150
	v_exp_f32_e32 v149, v149
	v_mul_f32_e32 v152, 0xbfb8aa3b, v159
	v_exp_f32_e32 v152, v152
	v_add_f32_e32 v149, 1.0, v149
	v_rcp_f32_e32 v149, v149
	v_add_f32_e32 v152, 1.0, v152
	v_rcp_f32_e32 v152, v152
	v_mul_f32_e32 v149, v150, v149
	v_mul_f32_e32 v150, 0xbfb8aa3b, v151
	v_exp_f32_e32 v150, v150
	v_mul_f32_e32 v149, v154, v149
	v_mul_f32_e32 v152, v159, v152
	v_mul_f32_e32 v152, v163, v152
	v_add_f32_e32 v150, 1.0, v150
	v_rcp_f32_e32 v150, v150
	s_nop 0
	v_mul_f32_e32 v150, v151, v150
	v_mul_f32_e32 v150, v155, v150
	v_cvt_pk_bf16_f32 v149, v149, v150
	v_mul_f32_e32 v150, 0xbfb8aa3b, v160
	v_mul_f32_e32 v151, 0xbfb8aa3b, v161
	v_exp_f32_e32 v150, v150
	v_exp_f32_e32 v151, v151
	v_add_f32_e32 v150, 1.0, v150
	v_add_f32_e32 v151, 1.0, v151
	v_rcp_f32_e32 v150, v150
	v_rcp_f32_e32 v151, v151
	v_mul_f32_e32 v150, v160, v150
	v_mul_f32_e32 v151, v161, v151
	v_mul_f32_e32 v150, v164, v150
	v_mul_f32_e32 v151, v165, v151
	v_cvt_pk_bf16_f32 v150, v150, v151
	v_mul_f32_e32 v151, 0xbfb8aa3b, v158
	v_exp_f32_e32 v151, v151
	s_nop 0
	v_add_f32_e32 v151, 1.0, v151
	v_rcp_f32_e32 v151, v151
	s_nop 0
	v_mul_f32_e32 v151, v158, v151
	v_mul_f32_e32 v151, v162, v151
	v_cvt_pk_bf16_f32 v151, v151, v152
	v_mad_i64_i32 v[152:153], s[4:5], v147, s33, v[136:137]
	v_lshl_add_u64 v[152:153], v[152:153], 0, v[138:139]
	global_store_dwordx4 v[152:153], v[148:151], off
	ds_read_b32 v148, v145 offset:192
	v_or_b32_e32 v147, 48, v146
	s_waitcnt lgkmcnt(0)
; __device__ __forceinline__ unsigned pk2(float lo, float hi) { unsigned r; asm volatile("v_cvt_pk_bf16_f32 %0, %1, %2" : "=v"(r) : "v"(lo), "v"(hi)); return r; }
; __device__ __forceinline__ float siluf_(float x) { return x * __builtin_amdgcn_rcpf(1.0f + __expf(-x)); }
;     template <int mode> __device__ __forceinline__ void run(const f32x4 (&acc)[2][2][4][2], const Unit& u, int wr, int wc, int fr, int fq, const LAS float* sc) const {
;     ...
;         if (mode == 0) {
;             const int col0 = u.pn * HALF + wc * 32 + 8 * fq;
; #pragma unroll
;             for (int ai = 0; ai < 2; ++ai)
; #pragma unroll
;                 for (int m = 0; m < 4; ++m) {
;                     const int row = row0 + ai * HALF + m * 16;
;                     const float s = sc[ai * HALF + wr * 64 + m * 16 + fr];
;                     const f32x4 g0 = acc[ai][0][m][0] * s, u0 = acc[ai][1][m][0] * s, g1 = acc[ai][0][m][1] * s, u1 = acc[ai][1][m][1] * s;
;                     u32x4 w;
;                     w.x = pk2(siluf_(g0[0]) * u0[0], siluf_(g0[1]) * u0[1]); w.y = pk2(siluf_(g0[2]) * u0[2], siluf_(g0[3]) * u0[3]);
;                     w.z = pk2(siluf_(g1[0]) * u1[0], siluf_(g1[1]) * u1[1]); w.w = pk2(siluf_(g1[2]) * u1[2], siluf_(g1[3]) * u1[3]);
;                     *(u32x4*)(ob + (size_t)row * FF + col0) = w;
;                 }
	v_pk_mul_f32 v[152:153], v[102:103], v[148:149] op_sel_hi:[1,0]
	v_pk_mul_f32 v[150:151], v[104:105], v[148:149] op_sel_hi:[1,0]
	v_pk_mul_f32 v[154:155], v[72:73], v[148:149] op_sel_hi:[1,0]
	v_pk_mul_f32 v[156:157], v[70:71], v[148:149] op_sel_hi:[1,0]
	v_pk_mul_f32 v[158:159], v[100:101], v[148:149] op_sel_hi:[1,0]
	v_pk_mul_f32 v[160:161], v[98:99], v[148:149] op_sel_hi:[1,0]
	v_pk_mul_f32 v[162:163], v[68:69], v[148:149] op_sel_hi:[1,0]
	v_pk_mul_f32 v[164:165], v[66:67], v[148:149] op_sel_hi:[1,0]
	v_mul_f32_e32 v148, 0xbfb8aa3b, v152
	v_mul_f32_e32 v149, 0xbfb8aa3b, v153
	v_exp_f32_e32 v148, v148
	v_exp_f32_e32 v149, v149
	v_add_f32_e32 v148, 1.0, v148
	v_add_f32_e32 v149, 1.0, v149
	v_rcp_f32_e32 v148, v148
	v_rcp_f32_e32 v149, v149
	v_mul_f32_e32 v148, v152, v148
	v_mul_f32_e32 v149, v153, v149
	v_mul_f32_e32 v148, v156, v148
	v_mul_f32_e32 v149, v157, v149
	v_cvt_pk_bf16_f32 v148, v148, v149
	v_mul_f32_e32 v149, 0xbfb8aa3b, v150
	v_exp_f32_e32 v149, v149
	v_mul_f32_e32 v152, 0xbfb8aa3b, v159
	v_exp_f32_e32 v152, v152
	v_add_f32_e32 v149, 1.0, v149
	v_rcp_f32_e32 v149, v149
	v_add_f32_e32 v152, 1.0, v152
	v_rcp_f32_e32 v152, v152
	v_mul_f32_e32 v149, v150, v149
	v_mul_f32_e32 v150, 0xbfb8aa3b, v151
	v_exp_f32_e32 v150, v150
	v_mul_f32_e32 v149, v154, v149
	v_mul_f32_e32 v152, v159, v152
	v_mul_f32_e32 v152, v163, v152
	v_add_f32_e32 v150, 1.0, v150
	v_rcp_f32_e32 v150, v150
	s_nop 0
	v_mul_f32_e32 v150, v151, v150
	v_mul_f32_e32 v150, v155, v150
	v_cvt_pk_bf16_f32 v149, v149, v150
	v_mul_f32_e32 v150, 0xbfb8aa3b, v160
	v_mul_f32_e32 v151, 0xbfb8aa3b, v161
	v_exp_f32_e32 v150, v150
	v_exp_f32_e32 v151, v151
	v_add_f32_e32 v150, 1.0, v150
	v_add_f32_e32 v151, 1.0, v151
	v_rcp_f32_e32 v150, v150
	v_rcp_f32_e32 v151, v151
	v_mul_f32_e32 v150, v160, v150
	v_mul_f32_e32 v151, v161, v151
	v_mul_f32_e32 v150, v164, v150
	v_mul_f32_e32 v151, v165, v151
	v_cvt_pk_bf16_f32 v150, v150, v151
	v_mul_f32_e32 v151, 0xbfb8aa3b, v158
	v_exp_f32_e32 v151, v151
	s_nop 0
	v_add_f32_e32 v151, 1.0, v151
	v_rcp_f32_e32 v151, v151
	s_nop 0
	v_mul_f32_e32 v151, v158, v151
	v_mul_f32_e32 v151, v162, v151
	v_cvt_pk_bf16_f32 v151, v151, v152
	v_mad_i64_i32 v[152:153], s[4:5], v147, s33, v[136:137]
	v_lshl_add_u64 v[152:153], v[152:153], 0, v[138:139]
	global_store_dwordx4 v[152:153], v[148:151], off
	ds_read_b32 v148, v145 offset:512
	v_add_u32_e32 v147, 0x80, v146
	s_waitcnt lgkmcnt(0)
	v_pk_mul_f32 v[152:153], v[62:63], v[148:149] op_sel_hi:[1,0]
	v_pk_mul_f32 v[150:151], v[64:65], v[148:149] op_sel_hi:[1,0]
	v_pk_mul_f32 v[154:155], v[32:33], v[148:149] op_sel_hi:[1,0]
	v_pk_mul_f32 v[156:157], v[30:31], v[148:149] op_sel_hi:[1,0]
	v_pk_mul_f32 v[158:159], v[60:61], v[148:149] op_sel_hi:[1,0]
	v_pk_mul_f32 v[160:161], v[58:59], v[148:149] op_sel_hi:[1,0]
	v_pk_mul_f32 v[162:163], v[28:29], v[148:149] op_sel_hi:[1,0]
	v_pk_mul_f32 v[164:165], v[26:27], v[148:149] op_sel_hi:[1,0]
	v_mul_f32_e32 v148, 0xbfb8aa3b, v152
	v_mul_f32_e32 v149, 0xbfb8aa3b, v153
	v_exp_f32_e32 v148, v148
	v_exp_f32_e32 v149, v149
	v_add_f32_e32 v148, 1.0, v148
	v_add_f32_e32 v149, 1.0, v149
	v_rcp_f32_e32 v148, v148
	v_rcp_f32_e32 v149, v149
	v_mul_f32_e32 v148, v152, v148
	v_mul_f32_e32 v149, v153, v149
	v_mul_f32_e32 v148, v156, v148
	v_mul_f32_e32 v149, v157, v149
	v_cvt_pk_bf16_f32 v148, v148, v149
	v_mul_f32_e32 v149, 0xbfb8aa3b, v150
	v_exp_f32_e32 v149, v149
	v_mul_f32_e32 v152, 0xbfb8aa3b, v159
	v_exp_f32_e32 v152, v152
	v_add_f32_e32 v149, 1.0, v149
	v_rcp_f32_e32 v149, v149
	v_add_f32_e32 v152, 1.0, v152
	v_rcp_f32_e32 v152, v152
	v_mul_f32_e32 v149, v150, v149
	v_mul_f32_e32 v150, 0xbfb8aa3b, v151
	v_exp_f32_e32 v150, v150
	v_mul_f32_e32 v149, v154, v149
	v_mul_f32_e32 v152, v159, v152
	v_mul_f32_e32 v152, v163, v152
	v_add_f32_e32 v150, 1.0, v150
	v_rcp_f32_e32 v150, v150
	s_nop 0
	v_mul_f32_e32 v150, v151, v150
	v_mul_f32_e32 v150, v155, v150
	v_cvt_pk_bf16_f32 v149, v149, v150
	v_mul_f32_e32 v150, 0xbfb8aa3b, v160
	v_mul_f32_e32 v151, 0xbfb8aa3b, v161
	v_exp_f32_e32 v150, v150
	v_exp_f32_e32 v151, v151
	v_add_f32_e32 v150, 1.0, v150
	v_add_f32_e32 v151, 1.0, v151
	v_rcp_f32_e32 v150, v150
	v_rcp_f32_e32 v151, v151
	v_mul_f32_e32 v150, v160, v150
	v_mul_f32_e32 v151, v161, v151
	v_mul_f32_e32 v150, v164, v150
	v_mul_f32_e32 v151, v165, v151
	v_cvt_pk_bf16_f32 v150, v150, v151
	v_mul_f32_e32 v151, 0xbfb8aa3b, v158
	v_exp_f32_e32 v151, v151
	s_nop 0
	v_add_f32_e32 v151, 1.0, v151
	v_rcp_f32_e32 v151, v151
	s_nop 0
	v_mul_f32_e32 v151, v158, v151
	v_mul_f32_e32 v151, v162, v151
	v_cvt_pk_bf16_f32 v151, v151, v152
	v_mad_i64_i32 v[152:153], s[4:5], v147, s33, v[136:137]
	v_lshl_add_u64 v[152:153], v[152:153], 0, v[138:139]
	global_store_dwordx4 v[152:153], v[148:151], off
	ds_read_b32 v148, v145 offset:576
	v_add_u32_e32 v147, 0x90, v146
	s_waitcnt lgkmcnt(0)
; __device__ __forceinline__ unsigned pk2(float lo, float hi) { unsigned r; asm volatile("v_cvt_pk_bf16_f32 %0, %1, %2" : "=v"(r) : "v"(lo), "v"(hi)); return r; }
; __device__ __forceinline__ float siluf_(float x) { return x * __builtin_amdgcn_rcpf(1.0f + __expf(-x)); }
;     template <int mode> __device__ __forceinline__ void run(const f32x4 (&acc)[2][2][4][2], const Unit& u, int wr, int wc, int fr, int fq, const LAS float* sc) const {
;     ...
;         if (mode == 0) {
;             const int col0 = u.pn * HALF + wc * 32 + 8 * fq;
; #pragma unroll
;             for (int ai = 0; ai < 2; ++ai)
; #pragma unroll
;                 for (int m = 0; m < 4; ++m) {
;                     const int row = row0 + ai * HALF + m * 16;
;                     const float s = sc[ai * HALF + wr * 64 + m * 16 + fr];
;                     const f32x4 g0 = acc[ai][0][m][0] * s, u0 = acc[ai][1][m][0] * s, g1 = acc[ai][0][m][1] * s, u1 = acc[ai][1][m][1] * s;
;                     u32x4 w;
;                     w.x = pk2(siluf_(g0[0]) * u0[0], siluf_(g0[1]) * u0[1]); w.y = pk2(siluf_(g0[2]) * u0[2], siluf_(g0[3]) * u0[3]);
;                     w.z = pk2(siluf_(g1[0]) * u1[0], siluf_(g1[1]) * u1[1]); w.w = pk2(siluf_(g1[2]) * u1[2], siluf_(g1[3]) * u1[3]);
;                     *(u32x4*)(ob + (size_t)row * FF + col0) = w;
;                 }
	v_pk_mul_f32 v[152:153], v[54:55], v[148:149] op_sel_hi:[1,0]
	v_pk_mul_f32 v[150:151], v[56:57], v[148:149] op_sel_hi:[1,0]
	v_pk_mul_f32 v[154:155], v[24:25], v[148:149] op_sel_hi:[1,0]
	v_pk_mul_f32 v[156:157], v[22:23], v[148:149] op_sel_hi:[1,0]
	v_pk_mul_f32 v[158:159], v[52:53], v[148:149] op_sel_hi:[1,0]
	v_pk_mul_f32 v[160:161], v[50:51], v[148:149] op_sel_hi:[1,0]
	v_pk_mul_f32 v[162:163], v[20:21], v[148:149] op_sel_hi:[1,0]
	v_pk_mul_f32 v[164:165], v[18:19], v[148:149] op_sel_hi:[1,0]
	v_mul_f32_e32 v148, 0xbfb8aa3b, v152
	v_mul_f32_e32 v149, 0xbfb8aa3b, v153
	v_exp_f32_e32 v148, v148
	v_exp_f32_e32 v149, v149
	v_add_f32_e32 v148, 1.0, v148
	v_add_f32_e32 v149, 1.0, v149
	v_rcp_f32_e32 v148, v148
	v_rcp_f32_e32 v149, v149
	v_mul_f32_e32 v148, v152, v148
	v_mul_f32_e32 v149, v153, v149
	v_mul_f32_e32 v148, v156, v148
	v_mul_f32_e32 v149, v157, v149
	v_cvt_pk_bf16_f32 v148, v148, v149
	v_mul_f32_e32 v149, 0xbfb8aa3b, v150
	v_exp_f32_e32 v149, v149
	v_mul_f32_e32 v152, 0xbfb8aa3b, v159
	v_exp_f32_e32 v152, v152
	v_add_f32_e32 v149, 1.0, v149
	v_rcp_f32_e32 v149, v149
	v_add_f32_e32 v152, 1.0, v152
	v_rcp_f32_e32 v152, v152
	v_mul_f32_e32 v149, v150, v149
	v_mul_f32_e32 v150, 0xbfb8aa3b, v151
	v_exp_f32_e32 v150, v150
	v_mul_f32_e32 v149, v154, v149
	v_mul_f32_e32 v152, v159, v152
	v_mul_f32_e32 v152, v163, v152
	v_add_f32_e32 v150, 1.0, v150
	v_rcp_f32_e32 v150, v150
	s_nop 0
	v_mul_f32_e32 v150, v151, v150
	v_mul_f32_e32 v150, v155, v150
	v_cvt_pk_bf16_f32 v149, v149, v150
	v_mul_f32_e32 v150, 0xbfb8aa3b, v160
	v_mul_f32_e32 v151, 0xbfb8aa3b, v161
	v_exp_f32_e32 v150, v150
	v_exp_f32_e32 v151, v151
	v_add_f32_e32 v150, 1.0, v150
	v_add_f32_e32 v151, 1.0, v151
	v_rcp_f32_e32 v150, v150
	v_rcp_f32_e32 v151, v151
	v_mul_f32_e32 v150, v160, v150
	v_mul_f32_e32 v151, v161, v151
	v_mul_f32_e32 v150, v164, v150
	v_mul_f32_e32 v151, v165, v151
	v_cvt_pk_bf16_f32 v150, v150, v151
	v_mul_f32_e32 v151, 0xbfb8aa3b, v158
	v_exp_f32_e32 v151, v151
	s_nop 0
	v_add_f32_e32 v151, 1.0, v151
	v_rcp_f32_e32 v151, v151
	s_nop 0
	v_mul_f32_e32 v151, v158, v151
	v_mul_f32_e32 v151, v162, v151
	v_cvt_pk_bf16_f32 v151, v151, v152
	v_mad_i64_i32 v[152:153], s[4:5], v147, s33, v[136:137]
	v_lshl_add_u64 v[152:153], v[152:153], 0, v[138:139]
	global_store_dwordx4 v[152:153], v[148:151], off
	ds_read_b32 v148, v145 offset:640
	v_add_u32_e32 v147, 0xa0, v146
	s_waitcnt lgkmcnt(0)
	v_pk_mul_f32 v[152:153], v[46:47], v[148:149] op_sel_hi:[1,0]
	v_pk_mul_f32 v[150:151], v[48:49], v[148:149] op_sel_hi:[1,0]
	v_pk_mul_f32 v[154:155], v[16:17], v[148:149] op_sel_hi:[1,0]
	v_pk_mul_f32 v[156:157], v[14:15], v[148:149] op_sel_hi:[1,0]
	v_pk_mul_f32 v[158:159], v[44:45], v[148:149] op_sel_hi:[1,0]
	v_pk_mul_f32 v[160:161], v[42:43], v[148:149] op_sel_hi:[1,0]
	v_pk_mul_f32 v[162:163], v[12:13], v[148:149] op_sel_hi:[1,0]
	v_pk_mul_f32 v[164:165], v[10:11], v[148:149] op_sel_hi:[1,0]
	v_mul_f32_e32 v148, 0xbfb8aa3b, v152
	v_mul_f32_e32 v149, 0xbfb8aa3b, v153
	v_exp_f32_e32 v148, v148
	v_exp_f32_e32 v149, v149
	v_add_f32_e32 v148, 1.0, v148
	v_add_f32_e32 v149, 1.0, v149
	v_rcp_f32_e32 v148, v148
	v_rcp_f32_e32 v149, v149
	v_mul_f32_e32 v148, v152, v148
	v_mul_f32_e32 v149, v153, v149
	v_mul_f32_e32 v148, v156, v148
	v_mul_f32_e32 v149, v157, v149
	v_cvt_pk_bf16_f32 v148, v148, v149
	v_mul_f32_e32 v149, 0xbfb8aa3b, v150
	v_exp_f32_e32 v149, v149
	v_mul_f32_e32 v152, 0xbfb8aa3b, v159
	v_exp_f32_e32 v152, v152
	v_add_f32_e32 v149, 1.0, v149
	v_rcp_f32_e32 v149, v149
	v_add_f32_e32 v152, 1.0, v152
	v_rcp_f32_e32 v152, v152
	v_mul_f32_e32 v149, v150, v149
	v_mul_f32_e32 v150, 0xbfb8aa3b, v151
	v_exp_f32_e32 v150, v150
	v_mul_f32_e32 v149, v154, v149
	v_mul_f32_e32 v152, v159, v152
	v_mul_f32_e32 v152, v163, v152
	v_add_f32_e32 v150, 1.0, v150
	v_rcp_f32_e32 v150, v150
	s_nop 0
	v_mul_f32_e32 v150, v151, v150
	v_mul_f32_e32 v150, v155, v150
	v_cvt_pk_bf16_f32 v149, v149, v150
	v_mul_f32_e32 v150, 0xbfb8aa3b, v160
	v_mul_f32_e32 v151, 0xbfb8aa3b, v161
	v_exp_f32_e32 v150, v150
	v_exp_f32_e32 v151, v151
	v_add_f32_e32 v150, 1.0, v150
	v_add_f32_e32 v151, 1.0, v151
	v_rcp_f32_e32 v150, v150
	v_rcp_f32_e32 v151, v151
	v_mul_f32_e32 v150, v160, v150
	v_mul_f32_e32 v151, v161, v151
	v_mul_f32_e32 v150, v164, v150
	v_mul_f32_e32 v151, v165, v151
	v_cvt_pk_bf16_f32 v150, v150, v151
	v_mul_f32_e32 v151, 0xbfb8aa3b, v158
	v_exp_f32_e32 v151, v151
	v_add_u32_e32 v164, 0xb0, v146
	v_add_f32_e32 v151, 1.0, v151
	v_rcp_f32_e32 v151, v151
	s_nop 0
	v_mul_f32_e32 v151, v158, v151
	v_mul_f32_e32 v151, v162, v151
	v_cvt_pk_bf16_f32 v151, v151, v152
	ds_read_b32 v146, v145 offset:704
	v_mad_i64_i32 v[152:153], s[4:5], v147, s33, v[136:137]
	v_lshl_add_u64 v[152:153], v[152:153], 0, v[138:139]
	global_store_dwordx4 v[152:153], v[148:151], off
	s_waitcnt lgkmcnt(0)
; __device__ __forceinline__ unsigned pk2(float lo, float hi) { unsigned r; asm volatile("v_cvt_pk_bf16_f32 %0, %1, %2" : "=v"(r) : "v"(lo), "v"(hi)); return r; }
; __device__ __forceinline__ float siluf_(float x) { return x * __builtin_amdgcn_rcpf(1.0f + __expf(-x)); }
;     template <int mode> __device__ __forceinline__ void run(const f32x4 (&acc)[2][2][4][2], const Unit& u, int wr, int wc, int fr, int fq, const LAS float* sc) const {
;     ...
;         if (mode == 0) {
;             const int col0 = u.pn * HALF + wc * 32 + 8 * fq;
; #pragma unroll
;             for (int ai = 0; ai < 2; ++ai)
; #pragma unroll
;                 for (int m = 0; m < 4; ++m) {
;                     const int row = row0 + ai * HALF + m * 16;
;                     const float s = sc[ai * HALF + wr * 64 + m * 16 + fr];
;                     const f32x4 g0 = acc[ai][0][m][0] * s, u0 = acc[ai][1][m][0] * s, g1 = acc[ai][0][m][1] * s, u1 = acc[ai][1][m][1] * s;
;                     u32x4 w;
;                     w.x = pk2(siluf_(g0[0]) * u0[0], siluf_(g0[1]) * u0[1]); w.y = pk2(siluf_(g0[2]) * u0[2], siluf_(g0[3]) * u0[3]);
;                     w.z = pk2(siluf_(g1[0]) * u1[0], siluf_(g1[1]) * u1[1]); w.w = pk2(siluf_(g1[2]) * u1[2], siluf_(g1[3]) * u1[3]);
;                     *(u32x4*)(ob + (size_t)row * FF + col0) = w;
;                 }
; template <int MODE, class EpiT, class Sched>
; __device__ __forceinline__ void gemm_phase(LAS unsigned char* lds, const Gemm g, const Sched& S, const EpiT& E) {
;     ...
;         E.template run<MODE>(acc, cur, wr, wc, fr, fq, SC + ui * 256);
;         if (!has_next) break;
; #pragma unroll
;         for (int a = 0; a < 2; ++a)
; #pragma unroll
;             for (int b = 0; b < 2; ++b)
; #pragma unroll
;                 for (int m = 0; m < 4; ++m)
; #pragma unroll
;                     for (int n = 0; n < 2; ++n) acc[a][b][m][n] = (f32x4){0.f, 0.f, 0.f, 0.f};
;         cur = nxt; cA = nA; cB = nB; ++ui;
	v_pk_mul_f32 v[152:153], v[8:9], v[146:147] op_sel_hi:[1,0]
	v_pk_mul_f32 v[154:155], v[6:7], v[146:147] op_sel_hi:[1,0]
	v_pk_mul_f32 v[150:151], v[38:39], v[146:147] op_sel_hi:[1,0]
	v_pk_mul_f32 v[148:149], v[40:41], v[146:147] op_sel_hi:[1,0]
	v_pk_mul_f32 v[156:157], v[36:37], v[146:147] op_sel_hi:[1,0]
	v_pk_mul_f32 v[158:159], v[34:35], v[146:147] op_sel_hi:[1,0]
	v_pk_mul_f32 v[160:161], v[4:5], v[146:147] op_sel_hi:[1,0]
	v_pk_mul_f32 v[162:163], v[2:3], v[146:147] op_sel_hi:[1,0]
	v_mul_f32_e32 v145, 0xbfb8aa3b, v150
	v_mul_f32_e32 v146, 0xbfb8aa3b, v151
	v_exp_f32_e32 v145, v145
	v_exp_f32_e32 v146, v146
	v_mul_f32_e32 v147, 0xbfb8aa3b, v149
	v_exp_f32_e32 v147, v147
	v_add_f32_e32 v145, 1.0, v145
	v_add_f32_e32 v146, 1.0, v146
	v_rcp_f32_e32 v145, v145
	v_rcp_f32_e32 v146, v146
	v_add_f32_e32 v147, 1.0, v147
	v_rcp_f32_e32 v147, v147
	v_mul_f32_e32 v145, v150, v145
	v_mul_f32_e32 v146, v151, v146
	v_mul_f32_e32 v145, v154, v145
	v_mul_f32_e32 v146, v155, v146
	v_cvt_pk_bf16_f32 v146, v145, v146
	v_mul_f32_e32 v145, 0xbfb8aa3b, v148
	v_exp_f32_e32 v145, v145
	v_mul_f32_e32 v147, v149, v147
	v_mul_f32_e32 v147, v153, v147
	v_mul_f32_e32 v149, 0xbfb8aa3b, v157
	v_add_f32_e32 v145, 1.0, v145
	v_rcp_f32_e32 v145, v145
	v_exp_f32_e32 v149, v149
	v_mad_i64_i32 v[136:137], s[4:5], v164, s33, v[136:137]
	v_mul_f32_e32 v145, v148, v145
	v_mul_f32_e32 v145, v152, v145
	v_cvt_pk_bf16_f32 v147, v145, v147
	v_mul_f32_e32 v145, 0xbfb8aa3b, v158
	v_mul_f32_e32 v148, 0xbfb8aa3b, v159
	v_exp_f32_e32 v145, v145
	v_exp_f32_e32 v148, v148
	v_add_f32_e32 v149, 1.0, v149
	v_rcp_f32_e32 v149, v149
	v_add_f32_e32 v145, 1.0, v145
	v_add_f32_e32 v148, 1.0, v148
	v_rcp_f32_e32 v145, v145
	v_rcp_f32_e32 v148, v148
	v_mul_f32_e32 v149, v157, v149
	v_mul_f32_e32 v149, v161, v149
	v_mul_f32_e32 v145, v158, v145
	v_mul_f32_e32 v148, v159, v148
	v_mul_f32_e32 v145, v162, v145
	v_mul_f32_e32 v148, v163, v148
	v_cvt_pk_bf16_f32 v148, v145, v148
	v_mul_f32_e32 v145, 0xbfb8aa3b, v156
	v_exp_f32_e32 v145, v145
	v_lshl_add_u64 v[136:137], v[136:137], 0, v[138:139]
	v_add_f32_e32 v145, 1.0, v145
	v_rcp_f32_e32 v145, v145
	s_nop 0
	v_mul_f32_e32 v145, v156, v145
	v_mul_f32_e32 v145, v160, v145
	v_cvt_pk_bf16_f32 v149, v145, v149
	global_store_dwordx4 v[136:137], v[146:149], off
	s_cbranch_vccnz .LBB0_324
	v_mov_b32_e32 v2, 0
	s_mov_b32 s9, s61
	s_mov_b32 s8, s60
	s_mov_b64 s[12:13], s[28:29]
	s_mov_b64 s[10:11], s[34:35]
	s_mov_b32 s57, s2
	v_mov_b32_e32 v3, v2
	v_mov_b32_e32 v4, v2
	v_mov_b32_e32 v5, v2
	v_mov_b32_e32 v6, v2
	v_mov_b32_e32 v7, v2
	v_mov_b32_e32 v8, v2
	v_mov_b32_e32 v9, v2
	v_mov_b32_e32 v10, v2
	v_mov_b32_e32 v11, v2
	v_mov_b32_e32 v12, v2
	v_mov_b32_e32 v13, v2
	v_mov_b32_e32 v14, v2
	v_mov_b32_e32 v15, v2
	v_mov_b32_e32 v16, v2
	v_mov_b32_e32 v17, v2
	v_mov_b32_e32 v18, v2
	v_mov_b32_e32 v19, v2
	v_mov_b32_e32 v20, v2
	v_mov_b32_e32 v21, v2
	v_mov_b32_e32 v22, v2
	v_mov_b32_e32 v23, v2
	v_mov_b32_e32 v24, v2
	v_mov_b32_e32 v25, v2
	v_mov_b32_e32 v26, v2
	v_mov_b32_e32 v27, v2
	v_mov_b32_e32 v28, v2
	v_mov_b32_e32 v29, v2
	v_mov_b32_e32 v30, v2
	v_mov_b32_e32 v31, v2
	v_mov_b32_e32 v32, v2
	v_mov_b32_e32 v33, v2
	v_mov_b32_e32 v34, v2
	v_mov_b32_e32 v35, v2
	v_mov_b32_e32 v36, v2
	v_mov_b32_e32 v37, v2
	v_mov_b32_e32 v38, v2
	v_mov_b32_e32 v39, v2
	v_mov_b32_e32 v40, v2
	v_mov_b32_e32 v41, v2
	v_mov_b32_e32 v42, v2
	v_mov_b32_e32 v43, v2
	v_mov_b32_e32 v44, v2
	v_mov_b32_e32 v45, v2
	v_mov_b32_e32 v46, v2
	v_mov_b32_e32 v47, v2
	v_mov_b32_e32 v48, v2
	v_mov_b32_e32 v49, v2
	v_mov_b32_e32 v50, v2
	v_mov_b32_e32 v51, v2
	v_mov_b32_e32 v52, v2
	v_mov_b32_e32 v53, v2
	v_mov_b32_e32 v54, v2
	v_mov_b32_e32 v55, v2
	v_mov_b32_e32 v56, v2
	v_mov_b32_e32 v57, v2
	v_mov_b32_e32 v58, v2
	v_mov_b32_e32 v59, v2
	v_mov_b32_e32 v60, v2
	v_mov_b32_e32 v61, v2
	v_mov_b32_e32 v62, v2
	v_mov_b32_e32 v63, v2
	v_mov_b32_e32 v64, v2
	v_mov_b32_e32 v65, v2
	v_mov_b32_e32 v66, v2
	v_mov_b32_e32 v67, v2
	v_mov_b32_e32 v68, v2
	v_mov_b32_e32 v69, v2
	v_mov_b32_e32 v70, v2
	v_mov_b32_e32 v71, v2
	v_mov_b32_e32 v72, v2
	v_mov_b32_e32 v73, v2
	v_mov_b32_e32 v74, v2
	v_mov_b32_e32 v75, v2
	v_mov_b32_e32 v76, v2
	v_mov_b32_e32 v77, v2
	v_mov_b32_e32 v78, v2
	v_mov_b32_e32 v79, v2
	v_mov_b32_e32 v80, v2
	v_mov_b32_e32 v81, v2
	v_mov_b32_e32 v82, v2
	v_mov_b32_e32 v83, v2
	v_mov_b32_e32 v84, v2
	v_mov_b32_e32 v85, v2
	v_mov_b32_e32 v86, v2
	v_mov_b32_e32 v87, v2
	v_mov_b32_e32 v88, v2
	v_mov_b32_e32 v89, v2
	v_mov_b32_e32 v90, v2
	v_mov_b32_e32 v91, v2
	v_mov_b32_e32 v92, v2
	v_mov_b32_e32 v93, v2
	v_mov_b32_e32 v94, v2
	v_mov_b32_e32 v95, v2
	v_mov_b32_e32 v96, v2
	v_mov_b32_e32 v97, v2
	v_mov_b32_e32 v98, v2
	v_mov_b32_e32 v99, v2
	v_mov_b32_e32 v100, v2
	v_mov_b32_e32 v101, v2
	v_mov_b32_e32 v102, v2
	v_mov_b32_e32 v103, v2
	v_mov_b32_e32 v104, v2
	v_mov_b32_e32 v105, v2
	v_mov_b32_e32 v106, v2
	v_mov_b32_e32 v107, v2
	v_mov_b32_e32 v108, v2
	v_mov_b32_e32 v109, v2
	v_mov_b32_e32 v110, v2
	v_mov_b32_e32 v111, v2
	v_mov_b32_e32 v112, v2
	v_mov_b32_e32 v113, v2
	v_mov_b32_e32 v114, v2
	v_mov_b32_e32 v115, v2
	v_mov_b32_e32 v116, v2
	v_mov_b32_e32 v117, v2
	v_mov_b32_e32 v118, v2
	v_mov_b32_e32 v119, v2
	v_mov_b32_e32 v120, v2
	v_mov_b32_e32 v121, v2
	v_mov_b32_e32 v122, v2
	v_mov_b32_e32 v123, v2
	v_mov_b32_e32 v124, v2
	v_mov_b32_e32 v125, v2
	v_mov_b32_e32 v126, v2
	v_mov_b32_e32 v127, v2
	v_mov_b32_e32 v128, v2
	v_mov_b32_e32 v129, v2
	s_branch .LBB0_324

; __global__ void __launch_bounds__(NTHREADS, 2) mk_fwd(Params P_arg) {
	.amdhsa_kernel _Z6mk_fwd6Params
		.amdhsa_group_segment_fixed_size 0
		.amdhsa_private_segment_fixed_size 0
		.amdhsa_kernarg_size 544
		.amdhsa_user_sgpr_count 2
		.amdhsa_user_sgpr_dispatch_ptr 0
		.amdhsa_user_sgpr_queue_ptr 0
		.amdhsa_user_sgpr_kernarg_segment_ptr 1
		.amdhsa_user_sgpr_dispatch_id 0
		.amdhsa_user_sgpr_kernarg_preload_length 0
		.amdhsa_user_sgpr_kernarg_preload_offset 0
		.amdhsa_user_sgpr_private_segment_size 0
		.amdhsa_uses_dynamic_stack 0
		.amdhsa_enable_private_segment 0
		.amdhsa_system_sgpr_workgroup_id_x 1
		.amdhsa_system_sgpr_workgroup_id_y 0
		.amdhsa_system_sgpr_workgroup_id_z 0
		.amdhsa_system_sgpr_workgroup_info 0
		.amdhsa_system_vgpr_workitem_id 2
		.amdhsa_next_free_vgpr 252
		.amdhsa_next_free_sgpr 102
		.amdhsa_accum_offset 252
		.amdhsa_reserve_vcc 1
		.amdhsa_float_round_mode_32 0
		.amdhsa_float_round_mode_16_64 0
		.amdhsa_float_denorm_mode_32 3
		.amdhsa_float_denorm_mode_16_64 3
		.amdhsa_dx10_clamp 1
		.amdhsa_ieee_mode 1
		.amdhsa_fp16_overflow 0
		.amdhsa_tg_split 0
		.amdhsa_exception_fp_ieee_invalid_op 0
		.amdhsa_exception_fp_denorm_src 0
		.amdhsa_exception_fp_ieee_div_zero 0
		.amdhsa_exception_fp_ieee_overflow 0
		.amdhsa_exception_fp_ieee_underflow 0
		.amdhsa_exception_fp_ieee_inexact 0
		.amdhsa_exception_int_div_zero 0
	.end_amdhsa_kernel

; __global__ void __launch_bounds__(NTHREADS, 2) mk_fwd(Params P_arg) {
amdhsa.kernels:
  - .agpr_count:     0
    .args:
      - .offset:         0
        .size:           288
        .value_kind:     by_value
      - .offset:         288
        .size:           4
        .value_kind:     hidden_block_count_x
      - .offset:         292
        .size:           4
        .value_kind:     hidden_block_count_y
      - .offset:         296
        .size:           4
        .value_kind:     hidden_block_count_z
      - .offset:         300
        .size:           2
        .value_kind:     hidden_group_size_x
      - .offset:         302
        .size:           2
        .value_kind:     hidden_group_size_y
      - .offset:         304
        .size:           2
        .value_kind:     hidden_group_size_z
      - .offset:         306
        .size:           2
        .value_kind:     hidden_remainder_x
      - .offset:         308
        .size:           2
        .value_kind:     hidden_remainder_y
      - .offset:         310
        .size:           2
        .value_kind:     hidden_remainder_z
      - .offset:         328
        .size:           8
        .value_kind:     hidden_global_offset_x
      - .offset:         336
        .size:           8
        .value_kind:     hidden_global_offset_y
      - .offset:         344
        .size:           8
        .value_kind:     hidden_global_offset_z
      - .offset:         352
        .size:           2
        .value_kind:     hidden_grid_dims
      - .offset:         376
        .size:           8
        .value_kind:     hidden_multigrid_sync_arg
      - .offset:         408
        .size:           4
        .value_kind:     hidden_dynamic_lds_size
    .group_segment_fixed_size: 0
    .kernarg_segment_align: 8
    .kernarg_segment_size: 544
    .language:       OpenCL C
    .language_version:
      - 2
      - 0
    .max_flat_workgroup_size: 512
    .name:           _Z6mk_fwd6Params
    .private_segment_fixed_size: 0
    .sgpr_count:     108
    .sgpr_spill_count: 174
    .symbol:         _Z6mk_fwd6Params.kd
    .uniform_work_group_size: 1
    .uses_dynamic_stack: false
    .vgpr_count:     252
    .vgpr_spill_count: 0
    .wavefront_size: 64
